# merge-gate buffer stored in wave-blocked layout (coalesced EpiGate8 stores and EpiMerge loads)
# speedup vs baseline: 1.0048x; 1.0048x over previous
; __device__ __forceinline__ void row_rstd(const unsigned long long* ssq, int row0, float (&rs)[2][4]) {
;     ...
;     for (int ai = 0; ai < 2; ++ai)
; #pragma unroll
;         for (int m = 0; m < 4; ++m) q[ai][m] = ssq[row0 + ai * HALF + m * 16];
;     asm volatile("" : "+v"(q[0][0]), "+v"(q[0][1]), "+v"(q[0][2]), "+v"(q[0][3]), "+v"(q[1][0]), "+v"(q[1][1]), "+v"(q[1][2]), "+v"(q[1][3]));
; #pragma unroll
;     for (int ai = 0; ai < 2; ++ai)
; #pragma unroll
;         for (int m = 0; m < 4; ++m) {
;             const float qf = __builtin_fmaf((float)(unsigned)(q[ai][m] >> 32), 4294967296.0f, (float)(unsigned)q[ai][m]);
;             rs[ai][m] = __builtin_amdgcn_rsqf(__builtin_fmaf(qf, 1.0f / (SSQ_SCALE * DM), EPS)); }
;     template <int QVV> __device__ __forceinline__ void run(f32x4 (&acc)[2][2][4][2], const Unit& u, int wr, int wc, int fr, int fq) const {
;         constexpr int nai = (QVV == 2) ? 1 : 2; const int r0 = u.pm * BM + (QVV == 2 ? (u.seg - 1) * HALF : 0);
;         char* tb = (char*)(O + (size_t)r0 * NGC + u.pn * BM);
;         const int v = u.pm < 4 ? 4 : ((u.pm - 4) >> 5);
;         const char* swb = (const char*)(sw + (size_t)v * SWLD + u.pn * BM); const char* bmb = (const char*)(bm + u.pn * BM);
;         unsigned lo = (unsigned)((wr * 64 + fr) * NGC + wc * 32 + 8 * fq);
;         unsigned co = (unsigned)(wc * 32 + 8 * fq) * 4u;
;         asm volatile("" : "+v"(lo), "+v"(co));
;         float rs[2][4]; row_rstd(ssq, r0 + wr * 64 + fr, rs);
; #pragma unroll
;         for (int bj = 0; bj < 2; ++bj) {
;             const f32x4 s0 = (*(const f32x4*)(swb + co + bj * HALF * 4) + *(const f32x4*)(bmb + co + bj * HALF * 4)) * (-LOG2E) - 7.994353436858858f,
;                         s1 = (*(const f32x4*)(swb + co + bj * HALF * 4 + 16) + *(const f32x4*)(bmb + co + bj * HALF * 4 + 16)) * (-LOG2E) - 7.994353436858858f;
.LBB0_1279:
	s_mul_i32 s98, s53, 24
	s_add_i32 s98, s98, s52
	s_lshl_b32 s98, s98, 16
	s_add_u32 s98, s1, s98
	s_addc_u32 s99, s2, 0
	s_lshl_b32 s67, s53, 8
	v_add_u32_e32 v130, s67, v154
	v_ashrrev_i32_e32 v131, 31, v130
	v_and_b32_e32 v146, 0x1c0, v0
	v_lshlrev_b32_e32 v146, 7, v146
	v_and_b32_e32 v148, 48, v0
	v_lshl_or_b32 v146, v148, 4, v146
	v_and_b32_e32 v148, 15, v0
	v_lshl_or_b32 v146, v148, 3, v146
	v_mov_b32_e32 v159, v156
	v_lshl_add_u64 v[130:131], v[130:131], 3, s[44:45]
	global_load_dwordx2 v[132:133], v[130:131], off
	global_load_dwordx2 v[134:135], v[130:131], off offset:128
	global_load_dwordx2 v[136:137], v[130:131], off offset:256
	global_load_dwordx2 v[138:139], v[130:131], off offset:384
	global_load_dwordx2 v[140:141], v[130:131], off offset:1024
	global_load_dwordx2 v[142:143], v[130:131], off offset:1152
	global_load_dwordx2 v[144:145], v[130:131], off offset:1280
	s_nop 0
	global_load_dwordx2 v[130:131], v[130:131], off offset:1408
	s_mul_i32 s42, s53, 0x180000
	s_mul_hi_i32 s43, s67, 0x1800
	s_add_u32 s42, s1, s42
	s_addc_u32 s43, s2, s43
	s_lshl_b32 s52, s52, 8
	s_ashr_i32 s53, s52, 31
	s_add_u32 s42, s42, s52
	s_addc_u32 s43, s43, s53
	s_lshl_b64 s[30:31], s[30:31], 2
	s_add_u32 s62, s7, s30
	s_addc_u32 s63, s9, s31
	s_lshl_b64 s[30:31], s[52:53], 2
	s_add_u32 s62, s62, s30
	s_addc_u32 s63, s63, s31
	s_add_u32 s52, s3, s30
	s_flbit_i32_b32 s30, 0
	s_addc_u32 s53, s5, s31
	s_min_u32 s30, s30, 32
	s_sub_i32 s31, 32, s30
	v_mov_b32_e32 v147, v175
	s_waitcnt vmcnt(0)
	s_nop 0
	v_mov_b32_e32 v174, v133
	v_lshlrev_b64 v[148:149], s30, v[174:175]
	v_min_u32_e32 v133, 1, v148
	v_or_b32_e32 v133, v149, v133
	v_cvt_f32_u32_e32 v133, v133
	v_cvt_f32_u32_e32 v132, v132
	v_mov_b32_e32 v174, v135
	v_cvt_f32_u32_e32 v130, v130
	v_ldexp_f32 v133, v133, s31
	v_fmac_f32_e32 v132, 0x4f800000, v133
	v_fmamk_f32 v132, v132, 0x30000000, v231
	v_rsq_f32_e32 v168, v132
	v_lshlrev_b64 v[132:133], s30, v[174:175]
	v_min_u32_e32 v132, 1, v132
	v_or_b32_e32 v132, v133, v132
	v_cvt_f32_u32_e32 v132, v132
	v_cvt_f32_u32_e32 v133, v134
	v_mov_b32_e32 v174, v137
	v_lshl_add_u64 v[148:149], s[98:99], 0, v[146:147]
	v_ldexp_f32 v132, v132, s31
	v_fmac_f32_e32 v133, 0x4f800000, v132
	v_fmamk_f32 v132, v133, 0x30000000, v231
	v_rsq_f32_e32 v167, v132
	v_lshlrev_b64 v[132:133], s30, v[174:175]
	v_min_u32_e32 v132, 1, v132
	v_or_b32_e32 v132, v133, v132
	v_cvt_f32_u32_e32 v132, v132
	v_cvt_f32_u32_e32 v133, v136
	v_mov_b32_e32 v174, v139
	v_mul_f32_e32 v147, 0xbfb8aa3b, v168
	v_ldexp_f32 v132, v132, s31
	v_fmac_f32_e32 v133, 0x4f800000, v132
	v_fmamk_f32 v132, v133, 0x30000000, v231
	v_rsq_f32_e32 v166, v132
	v_lshlrev_b64 v[132:133], s30, v[174:175]
	v_min_u32_e32 v132, 1, v132
	v_or_b32_e32 v132, v133, v132
	v_cvt_f32_u32_e32 v132, v132
	v_cvt_f32_u32_e32 v133, v138
	v_mov_b32_e32 v174, v141
	v_ldexp_f32 v132, v132, s31
	v_fmac_f32_e32 v133, 0x4f800000, v132
	v_fmamk_f32 v132, v133, 0x30000000, v231
	v_rsq_f32_e32 v165, v132
	v_lshlrev_b64 v[132:133], s30, v[174:175]
	v_min_u32_e32 v132, 1, v132
	v_or_b32_e32 v132, v133, v132
	v_cvt_f32_u32_e32 v132, v132
	v_cvt_f32_u32_e32 v133, v140
	v_mov_b32_e32 v174, v143
	v_ldexp_f32 v132, v132, s31
	v_fmac_f32_e32 v133, 0x4f800000, v132
	v_fmamk_f32 v132, v133, 0x30000000, v231
	v_rsq_f32_e32 v164, v132
	v_lshlrev_b64 v[132:133], s30, v[174:175]
	v_min_u32_e32 v132, 1, v132
	v_or_b32_e32 v132, v133, v132
	v_cvt_f32_u32_e32 v132, v132
	v_cvt_f32_u32_e32 v133, v142
	v_mov_b32_e32 v174, v145
	v_ldexp_f32 v132, v132, s31
	v_fmac_f32_e32 v133, 0x4f800000, v132
	v_fmamk_f32 v132, v133, 0x30000000, v231
	v_rsq_f32_e32 v163, v132
	v_lshlrev_b64 v[132:133], s30, v[174:175]
	v_min_u32_e32 v132, 1, v132
	v_or_b32_e32 v132, v133, v132
	v_cvt_f32_u32_e32 v132, v132
	v_cvt_f32_u32_e32 v133, v144
	v_mov_b32_e32 v174, v131
	v_ldexp_f32 v132, v132, s31
	v_fmac_f32_e32 v133, 0x4f800000, v132
	v_fmamk_f32 v132, v133, 0x30000000, v231
	v_rsq_f32_e32 v161, v132
	v_lshlrev_b64 v[132:133], s30, v[174:175]
	v_min_u32_e32 v131, 1, v132
	v_or_b32_e32 v131, v133, v131
	v_cvt_f32_u32_e32 v131, v131
	s_mov_b32 s30, 0x400
	v_ldexp_f32 v131, v131, s31
	v_fmac_f32_e32 v130, 0x4f800000, v131
	v_fmamk_f32 v130, v130, 0x30000000, v231
	v_rsq_f32_e32 v160, v130
	global_load_dwordx4 v[130:133], v159, s[62:63] offset:16
	global_load_dwordx4 v[138:141], v159, s[62:63]
	global_load_dwordx4 v[134:137], v159, s[52:53] offset:16
	global_load_dwordx4 v[142:145], v159, s[52:53]
	s_waitcnt vmcnt(0)
;     template <int QVV> __device__ __forceinline__ void run(f32x4 (&acc)[2][2][4][2], const Unit& u, int wr, int wc, int fr, int fq) const {
;     ...
; #pragma unroll
;             for (int ai = 0; ai < 2; ++ai)
; #pragma unroll
;                 for (int m = 0; m < 4; ++m) { if (ai >= nai) continue;
;                     const float rn = rs[ai][m] * (-LOG2E);
;                     const f32x4 x0 = acc[ai][bj][m][0] * rn + s0, x1 = acc[ai][bj][m][1] * rn + s1;
;                     f32x4 d0, d1;
; #pragma unroll
;                     for (int i = 0; i < 4; ++i) { d0[i] = __builtin_amdgcn_exp2f(x0[i]); d1[i] = __builtin_amdgcn_exp2f(x1[i]); }
;                     d0 = d0 + (1.0f / 255.0f); d1 = d1 + (1.0f / 255.0f);
;                     u32x2 w = {0u, 0u};
; #pragma unroll
;                     for (int i = 0; i < 4; ++i) { const float g0 = fmaxf(__builtin_amdgcn_rcpf(d0[i]), 1.0f), g1 = fmaxf(__builtin_amdgcn_rcpf(d1[i]), 1.0f);
;                         w.x = __builtin_amdgcn_cvt_pk_u8_f32(g0, i, w.x); w.y = __builtin_amdgcn_cvt_pk_u8_f32(g1, i, w.y); }
;                     *(u32x2*)(tb + lo + (unsigned)((ai * HALF + m * 16) * NGC + bj * HALF)) = w; }
	v_add_f32_e32 v138, v138, v142
	v_fmamk_f32 v138, v138, 0xbfb8aa3b, v236
	v_fma_f32 v126, v126, v147, v138
	v_exp_f32_e32 v142, v126
	v_add_f32_e32 v126, v130, v134
	v_fmamk_f32 v126, v126, 0xbfb8aa3b, v236
	v_fma_f32 v122, v122, v147, v126
	v_exp_f32_e32 v134, v122
	v_add_f32_e32 v122, v139, v143
	v_fmamk_f32 v130, v122, 0xbfb8aa3b, v236
	v_fma_f32 v122, v127, v147, v130
	v_exp_f32_e32 v143, v122
	v_add_f32_e32 v122, v131, v135
	v_fmamk_f32 v127, v122, 0xbfb8aa3b, v236
	v_fma_f32 v122, v123, v147, v127
	v_exp_f32_e32 v135, v122
	v_add_f32_e32 v122, v140, v144
	v_fmamk_f32 v123, v122, 0xbfb8aa3b, v236
	v_fma_f32 v122, v128, v147, v123
	v_exp_f32_e32 v140, v122
	v_add_f32_e32 v122, v132, v136
	v_fmamk_f32 v128, v122, 0xbfb8aa3b, v236
	v_fma_f32 v122, v124, v147, v128
	v_exp_f32_e32 v132, v122
	v_add_f32_e32 v122, v141, v145
	v_fmamk_f32 v124, v122, 0xbfb8aa3b, v236
	v_fma_f32 v122, v129, v147, v124
	v_exp_f32_e32 v141, v122
	v_add_f32_e32 v122, v133, v137
	v_fmamk_f32 v129, v122, 0xbfb8aa3b, v236
	v_fma_f32 v122, v125, v147, v129
	v_pk_add_f32 v[136:137], v[140:141], s[0:1] op_sel_hi:[1,0]
	v_pk_add_f32 v[140:141], v[142:143], s[0:1] op_sel_hi:[1,0]
	v_exp_f32_e32 v133, v122
	v_rcp_f32_e32 v122, v140
	v_rcp_f32_e32 v131, v141
	v_pk_add_f32 v[134:135], v[134:135], s[0:1] op_sel_hi:[1,0]
	v_pk_add_f32 v[132:133], v[132:133], s[0:1] op_sel_hi:[1,0]
	v_max_f32_e32 v122, 1.0, v122
	v_rcp_f32_e32 v125, v134
	v_cvt_pk_u8_f32 v122, v122, 0, 0
	v_max_f32_e32 v131, 1.0, v131
	v_rcp_f32_e32 v134, v135
	v_cvt_pk_u8_f32 v122, v131, 1, v122
	v_rcp_f32_e32 v131, v136
	v_rcp_f32_e32 v132, v132
	v_max_f32_e32 v125, 1.0, v125
	v_cvt_pk_u8_f32 v125, v125, 0, 0
	v_max_f32_e32 v134, 1.0, v134
	v_max_f32_e32 v131, 1.0, v131
	v_cvt_pk_u8_f32 v125, v134, 1, v125
	v_max_f32_e32 v132, 1.0, v132
	v_cvt_pk_u8_f32 v122, v131, 2, v122
	v_rcp_f32_e32 v131, v137
	v_cvt_pk_u8_f32 v125, v132, 2, v125
	v_rcp_f32_e32 v132, v133
	v_max_f32_e32 v131, 1.0, v131
	v_max_f32_e32 v133, 1.0, v132
	v_cvt_pk_u8_f32 v132, v131, 3, v122
	v_mul_f32_e32 v122, 0xbfb8aa3b, v167
	v_fma_f32 v114, v114, v122, v126
	v_fma_f32 v115, v115, v122, v127
	v_exp_f32_e32 v114, v114
	v_exp_f32_e32 v115, v115
	v_fma_f32 v116, v116, v122, v128
	v_fma_f32 v117, v117, v122, v129
	v_exp_f32_e32 v116, v116
	v_exp_f32_e32 v117, v117
	v_fma_f32 v118, v118, v122, v138
	v_fma_f32 v119, v119, v122, v130
	v_exp_f32_e32 v118, v118
	v_exp_f32_e32 v119, v119
	v_pk_add_f32 v[114:115], v[114:115], s[0:1] op_sel_hi:[1,0]
	v_fma_f32 v120, v120, v122, v123
	v_fma_f32 v121, v121, v122, v124
	v_rcp_f32_e32 v114, v114
	v_exp_f32_e32 v120, v120
	v_exp_f32_e32 v121, v121
	v_pk_add_f32 v[116:117], v[116:117], s[0:1] op_sel_hi:[1,0]
	v_rcp_f32_e32 v115, v115
	v_rcp_f32_e32 v116, v116
	v_pk_add_f32 v[118:119], v[118:119], s[0:1] op_sel_hi:[1,0]
	v_max_f32_e32 v114, 1.0, v114
	v_rcp_f32_e32 v118, v118
	v_pk_add_f32 v[120:121], v[120:121], s[0:1] op_sel_hi:[1,0]
	v_cvt_pk_u8_f32 v114, v114, 0, 0
	v_rcp_f32_e32 v119, v119
	v_max_f32_e32 v115, 1.0, v115
	v_cvt_pk_u8_f32 v114, v115, 1, v114
	v_rcp_f32_e32 v115, v120
	v_max_f32_e32 v116, 1.0, v116
	v_rcp_f32_e32 v117, v117
	v_cvt_pk_u8_f32 v114, v116, 2, v114
	v_rcp_f32_e32 v116, v121
	v_max_f32_e32 v118, 1.0, v118
	v_cvt_pk_u8_f32 v118, v118, 0, 0
	v_max_f32_e32 v119, 1.0, v119
	v_cvt_pk_u8_f32 v118, v119, 1, v118
	v_max_f32_e32 v115, 1.0, v115
	v_max_f32_e32 v117, 1.0, v117
	v_cvt_pk_u8_f32 v115, v115, 2, v118
	v_max_f32_e32 v116, 1.0, v116
	v_cvt_pk_u8_f32 v117, v117, 3, v114
	v_add_co_u32_e32 v114, vcc, s30, v148
	v_cvt_pk_u8_f32 v116, v116, 3, v115
	s_nop 0
	v_addc_co_u32_e32 v115, vcc, 0, v149, vcc
	global_store_dwordx2 v[114:115], v[116:117], off
	v_mul_f32_e32 v116, 0xbfb8aa3b, v166
	v_fma_f32 v106, v106, v116, v126
	v_fma_f32 v107, v107, v116, v127
	v_exp_f32_e32 v106, v106
	v_exp_f32_e32 v107, v107
	v_fma_f32 v108, v108, v116, v128
	v_fma_f32 v109, v109, v116, v129
	v_exp_f32_e32 v108, v108
	v_exp_f32_e32 v109, v109
	v_fma_f32 v110, v110, v116, v138
	v_fma_f32 v111, v111, v116, v130
	v_exp_f32_e32 v110, v110
	v_exp_f32_e32 v111, v111
	v_pk_add_f32 v[106:107], v[106:107], s[0:1] op_sel_hi:[1,0]
	v_fma_f32 v112, v112, v116, v123
	v_fma_f32 v113, v113, v116, v124
	v_rcp_f32_e32 v106, v106
	v_exp_f32_e32 v112, v112
	v_exp_f32_e32 v113, v113
	v_pk_add_f32 v[108:109], v[108:109], s[0:1] op_sel_hi:[1,0]
	v_rcp_f32_e32 v107, v107
	v_rcp_f32_e32 v108, v108
	v_pk_add_f32 v[110:111], v[110:111], s[0:1] op_sel_hi:[1,0]
	v_max_f32_e32 v106, 1.0, v106
	v_rcp_f32_e32 v110, v110
	v_pk_add_f32 v[112:113], v[112:113], s[0:1] op_sel_hi:[1,0]
	v_cvt_pk_u8_f32 v106, v106, 0, 0
	v_rcp_f32_e32 v111, v111
	v_max_f32_e32 v107, 1.0, v107
	v_cvt_pk_u8_f32 v106, v107, 1, v106
	v_rcp_f32_e32 v107, v112
	v_max_f32_e32 v108, 1.0, v108
	v_rcp_f32_e32 v109, v109
	v_cvt_pk_u8_f32 v106, v108, 2, v106
	v_rcp_f32_e32 v108, v113
	v_max_f32_e32 v110, 1.0, v110
	v_cvt_pk_u8_f32 v110, v110, 0, 0
	v_max_f32_e32 v111, 1.0, v111
	v_cvt_pk_u8_f32 v110, v111, 1, v110
	v_max_f32_e32 v107, 1.0, v107
	v_max_f32_e32 v109, 1.0, v109
	s_mov_b32 s30, 0x800
	v_cvt_pk_u8_f32 v107, v107, 2, v110
	v_max_f32_e32 v108, 1.0, v108
	v_cvt_pk_u8_f32 v109, v109, 3, v106
	v_add_co_u32_e32 v106, vcc, s30, v148
	v_cvt_pk_u8_f32 v108, v108, 3, v107
	s_nop 0
	v_addc_co_u32_e32 v107, vcc, 0, v149, vcc
	global_store_dwordx2 v[106:107], v[108:109], off
	v_mul_f32_e32 v108, 0xbfb8aa3b, v165
	v_fma_f32 v98, v98, v108, v126
	v_fma_f32 v99, v99, v108, v127
	v_exp_f32_e32 v98, v98
	v_exp_f32_e32 v99, v99
	v_fma_f32 v100, v100, v108, v128
	v_fma_f32 v101, v101, v108, v129
	v_exp_f32_e32 v100, v100
	v_exp_f32_e32 v101, v101
	v_fma_f32 v102, v102, v108, v138
;     template <int QVV> __device__ __forceinline__ void run(f32x4 (&acc)[2][2][4][2], const Unit& u, int wr, int wc, int fr, int fq) const {
;     ...
; #pragma unroll
;             for (int ai = 0; ai < 2; ++ai)
; #pragma unroll
;                 for (int m = 0; m < 4; ++m) { if (ai >= nai) continue;
;                     const float rn = rs[ai][m] * (-LOG2E);
;                     const f32x4 x0 = acc[ai][bj][m][0] * rn + s0, x1 = acc[ai][bj][m][1] * rn + s1;
;                     f32x4 d0, d1;
; #pragma unroll
;                     for (int i = 0; i < 4; ++i) { d0[i] = __builtin_amdgcn_exp2f(x0[i]); d1[i] = __builtin_amdgcn_exp2f(x1[i]); }
;                     d0 = d0 + (1.0f / 255.0f); d1 = d1 + (1.0f / 255.0f);
;                     u32x2 w = {0u, 0u};
; #pragma unroll
;                     for (int i = 0; i < 4; ++i) { const float g0 = fmaxf(__builtin_amdgcn_rcpf(d0[i]), 1.0f), g1 = fmaxf(__builtin_amdgcn_rcpf(d1[i]), 1.0f);
;                         w.x = __builtin_amdgcn_cvt_pk_u8_f32(g0, i, w.x); w.y = __builtin_amdgcn_cvt_pk_u8_f32(g1, i, w.y); }
;                     *(u32x2*)(tb + lo + (unsigned)((ai * HALF + m * 16) * NGC + bj * HALF)) = w; }
	v_fma_f32 v103, v103, v108, v130
	v_exp_f32_e32 v102, v102
	v_exp_f32_e32 v103, v103
	v_pk_add_f32 v[98:99], v[98:99], s[0:1] op_sel_hi:[1,0]
	v_fma_f32 v104, v104, v108, v123
	v_fma_f32 v105, v105, v108, v124
	v_rcp_f32_e32 v98, v98
	v_exp_f32_e32 v104, v104
	v_exp_f32_e32 v105, v105
	v_pk_add_f32 v[100:101], v[100:101], s[0:1] op_sel_hi:[1,0]
	v_rcp_f32_e32 v99, v99
	v_rcp_f32_e32 v100, v100
	v_pk_add_f32 v[102:103], v[102:103], s[0:1] op_sel_hi:[1,0]
	v_max_f32_e32 v98, 1.0, v98
	v_rcp_f32_e32 v102, v102
	v_pk_add_f32 v[104:105], v[104:105], s[0:1] op_sel_hi:[1,0]
	v_cvt_pk_u8_f32 v98, v98, 0, 0
	v_rcp_f32_e32 v103, v103
	v_max_f32_e32 v99, 1.0, v99
	v_cvt_pk_u8_f32 v98, v99, 1, v98
	v_rcp_f32_e32 v99, v104
	v_max_f32_e32 v100, 1.0, v100
	v_rcp_f32_e32 v101, v101
	v_cvt_pk_u8_f32 v98, v100, 2, v98
	v_rcp_f32_e32 v100, v105
	v_max_f32_e32 v102, 1.0, v102
	v_cvt_pk_u8_f32 v102, v102, 0, 0
	v_max_f32_e32 v103, 1.0, v103
	v_cvt_pk_u8_f32 v102, v103, 1, v102
	v_max_f32_e32 v99, 1.0, v99
	v_max_f32_e32 v101, 1.0, v101
	s_mov_b32 s30, 0xc00
	v_cvt_pk_u8_f32 v99, v99, 2, v102
	v_max_f32_e32 v100, 1.0, v100
	v_cvt_pk_u8_f32 v101, v101, 3, v98
	v_add_co_u32_e32 v98, vcc, s30, v148
	v_cvt_pk_u8_f32 v100, v100, 3, v99
	s_nop 0
	v_addc_co_u32_e32 v99, vcc, 0, v149, vcc
	global_store_dwordx2 v[98:99], v[100:101], off
	v_mul_f32_e32 v100, 0xbfb8aa3b, v164
	v_fma_f32 v90, v90, v100, v126
	v_fma_f32 v91, v91, v100, v127
	v_exp_f32_e32 v90, v90
	v_exp_f32_e32 v91, v91
	v_fma_f32 v92, v92, v100, v128
	v_fma_f32 v93, v93, v100, v129
	v_exp_f32_e32 v92, v92
	v_exp_f32_e32 v93, v93
	v_fma_f32 v94, v94, v100, v138
	v_fma_f32 v95, v95, v100, v130
	v_exp_f32_e32 v94, v94
	v_exp_f32_e32 v95, v95
	v_pk_add_f32 v[90:91], v[90:91], s[0:1] op_sel_hi:[1,0]
	v_fma_f32 v96, v96, v100, v123
	v_fma_f32 v97, v97, v100, v124
	v_rcp_f32_e32 v90, v90
	v_exp_f32_e32 v96, v96
	v_exp_f32_e32 v97, v97
	v_pk_add_f32 v[92:93], v[92:93], s[0:1] op_sel_hi:[1,0]
	v_rcp_f32_e32 v91, v91
	v_rcp_f32_e32 v92, v92
	v_pk_add_f32 v[94:95], v[94:95], s[0:1] op_sel_hi:[1,0]
	v_max_f32_e32 v90, 1.0, v90
	v_rcp_f32_e32 v94, v94
	v_pk_add_f32 v[96:97], v[96:97], s[0:1] op_sel_hi:[1,0]
	v_cvt_pk_u8_f32 v90, v90, 0, 0
	v_rcp_f32_e32 v95, v95
	v_max_f32_e32 v91, 1.0, v91
	v_cvt_pk_u8_f32 v90, v91, 1, v90
	v_rcp_f32_e32 v91, v96
	v_max_f32_e32 v92, 1.0, v92
	v_rcp_f32_e32 v93, v93
	v_cvt_pk_u8_f32 v90, v92, 2, v90
	v_rcp_f32_e32 v92, v97
	v_max_f32_e32 v94, 1.0, v94
	v_cvt_pk_u8_f32 v94, v94, 0, 0
	v_max_f32_e32 v95, 1.0, v95
	v_cvt_pk_u8_f32 v94, v95, 1, v94
	v_max_f32_e32 v91, 1.0, v91
	v_max_f32_e32 v93, 1.0, v93
	s_mov_b32 s30, 0x1000
	v_cvt_pk_u8_f32 v91, v91, 2, v94
	v_max_f32_e32 v92, 1.0, v92
	v_cvt_pk_u8_f32 v93, v93, 3, v90
	v_add_co_u32_e32 v90, vcc, s30, v148
	v_cvt_pk_u8_f32 v92, v92, 3, v91
	s_nop 0
	v_addc_co_u32_e32 v91, vcc, 0, v149, vcc
	global_store_dwordx2 v[90:91], v[92:93], off
	v_mul_f32_e32 v92, 0xbfb8aa3b, v163
	v_fma_f32 v82, v82, v92, v126
	v_fma_f32 v83, v83, v92, v127
	v_exp_f32_e32 v82, v82
	v_exp_f32_e32 v83, v83
	v_fma_f32 v84, v84, v92, v128
	v_fma_f32 v85, v85, v92, v129
	v_exp_f32_e32 v84, v84
	v_exp_f32_e32 v85, v85
	v_fma_f32 v86, v86, v92, v138
	v_fma_f32 v87, v87, v92, v130
	v_exp_f32_e32 v86, v86
	v_exp_f32_e32 v87, v87
	v_pk_add_f32 v[82:83], v[82:83], s[0:1] op_sel_hi:[1,0]
	v_fma_f32 v88, v88, v92, v123
	v_fma_f32 v89, v89, v92, v124
	v_rcp_f32_e32 v82, v82
	v_exp_f32_e32 v88, v88
	v_exp_f32_e32 v89, v89
	v_pk_add_f32 v[84:85], v[84:85], s[0:1] op_sel_hi:[1,0]
	v_rcp_f32_e32 v83, v83
	v_rcp_f32_e32 v84, v84
	v_pk_add_f32 v[86:87], v[86:87], s[0:1] op_sel_hi:[1,0]
	v_max_f32_e32 v82, 1.0, v82
	v_rcp_f32_e32 v86, v86
	v_pk_add_f32 v[88:89], v[88:89], s[0:1] op_sel_hi:[1,0]
	v_cvt_pk_u8_f32 v82, v82, 0, 0
	v_rcp_f32_e32 v87, v87
	v_max_f32_e32 v83, 1.0, v83
	v_cvt_pk_u8_f32 v82, v83, 1, v82
	v_rcp_f32_e32 v83, v88
	v_max_f32_e32 v84, 1.0, v84
	v_rcp_f32_e32 v85, v85
	v_cvt_pk_u8_f32 v82, v84, 2, v82
	v_rcp_f32_e32 v84, v89
	v_max_f32_e32 v86, 1.0, v86
	v_cvt_pk_u8_f32 v86, v86, 0, 0
	v_max_f32_e32 v87, 1.0, v87
	v_cvt_pk_u8_f32 v86, v87, 1, v86
	v_max_f32_e32 v83, 1.0, v83
	v_max_f32_e32 v85, 1.0, v85
	s_mov_b32 s30, 0x1400
	v_cvt_pk_u8_f32 v83, v83, 2, v86
	v_max_f32_e32 v84, 1.0, v84
	v_cvt_pk_u8_f32 v85, v85, 3, v82
	v_add_co_u32_e32 v82, vcc, s30, v148
	v_cvt_pk_u8_f32 v84, v84, 3, v83
	s_nop 0
	v_addc_co_u32_e32 v83, vcc, 0, v149, vcc
	global_store_dwordx2 v[82:83], v[84:85], off
	v_mul_f32_e32 v84, 0xbfb8aa3b, v161
	v_fma_f32 v74, v74, v84, v126
	v_fma_f32 v75, v75, v84, v127
	v_exp_f32_e32 v74, v74
	v_exp_f32_e32 v75, v75
	v_fma_f32 v76, v76, v84, v128
	v_fma_f32 v77, v77, v84, v129
	v_exp_f32_e32 v76, v76
	v_exp_f32_e32 v77, v77
	v_fma_f32 v78, v78, v84, v138
	v_fma_f32 v79, v79, v84, v130
	v_exp_f32_e32 v78, v78
	v_exp_f32_e32 v79, v79
	v_pk_add_f32 v[74:75], v[74:75], s[0:1] op_sel_hi:[1,0]
	v_fma_f32 v80, v80, v84, v123
	v_fma_f32 v81, v81, v84, v124
	v_rcp_f32_e32 v74, v74
	v_exp_f32_e32 v80, v80
	v_exp_f32_e32 v81, v81
	v_pk_add_f32 v[76:77], v[76:77], s[0:1] op_sel_hi:[1,0]
	v_rcp_f32_e32 v75, v75
	v_rcp_f32_e32 v76, v76
	v_pk_add_f32 v[78:79], v[78:79], s[0:1] op_sel_hi:[1,0]
	v_max_f32_e32 v74, 1.0, v74
	v_rcp_f32_e32 v78, v78
	v_pk_add_f32 v[80:81], v[80:81], s[0:1] op_sel_hi:[1,0]
	v_cvt_pk_u8_f32 v74, v74, 0, 0
	v_rcp_f32_e32 v79, v79
	v_max_f32_e32 v75, 1.0, v75
	v_cvt_pk_u8_f32 v74, v75, 1, v74
	v_rcp_f32_e32 v75, v80
	v_max_f32_e32 v76, 1.0, v76
	v_rcp_f32_e32 v77, v77
	v_cvt_pk_u8_f32 v74, v76, 2, v74
	v_rcp_f32_e32 v76, v81
	v_max_f32_e32 v78, 1.0, v78
	v_cvt_pk_u8_f32 v78, v78, 0, 0
	v_max_f32_e32 v79, 1.0, v79
	v_cvt_pk_u8_f32 v78, v79, 1, v78
;     template <int QVV> __device__ __forceinline__ void run(f32x4 (&acc)[2][2][4][2], const Unit& u, int wr, int wc, int fr, int fq) const {
;     ...
; #pragma unroll
;             for (int ai = 0; ai < 2; ++ai)
; #pragma unroll
;                 for (int m = 0; m < 4; ++m) { if (ai >= nai) continue;
;                     const float rn = rs[ai][m] * (-LOG2E);
;                     const f32x4 x0 = acc[ai][bj][m][0] * rn + s0, x1 = acc[ai][bj][m][1] * rn + s1;
;                     f32x4 d0, d1;
; #pragma unroll
;                     for (int i = 0; i < 4; ++i) { d0[i] = __builtin_amdgcn_exp2f(x0[i]); d1[i] = __builtin_amdgcn_exp2f(x1[i]); }
;                     d0 = d0 + (1.0f / 255.0f); d1 = d1 + (1.0f / 255.0f);
;                     u32x2 w = {0u, 0u};
; #pragma unroll
;                     for (int i = 0; i < 4; ++i) { const float g0 = fmaxf(__builtin_amdgcn_rcpf(d0[i]), 1.0f), g1 = fmaxf(__builtin_amdgcn_rcpf(d1[i]), 1.0f);
;                         w.x = __builtin_amdgcn_cvt_pk_u8_f32(g0, i, w.x); w.y = __builtin_amdgcn_cvt_pk_u8_f32(g1, i, w.y); }
;                     *(u32x2*)(tb + lo + (unsigned)((ai * HALF + m * 16) * NGC + bj * HALF)) = w; }
	v_max_f32_e32 v75, 1.0, v75
	v_max_f32_e32 v77, 1.0, v77
	s_mov_b32 s30, 0x1800
	v_cvt_pk_u8_f32 v75, v75, 2, v78
	v_max_f32_e32 v76, 1.0, v76
	v_cvt_pk_u8_f32 v77, v77, 3, v74
	v_add_co_u32_e32 v74, vcc, s30, v148
	v_cvt_pk_u8_f32 v76, v76, 3, v75
	s_nop 0
	v_addc_co_u32_e32 v75, vcc, 0, v149, vcc
	global_store_dwordx2 v[74:75], v[76:77], off
	v_mul_f32_e32 v76, 0xbfb8aa3b, v160
	v_fmac_f32_e32 v126, v66, v76
	v_fmac_f32_e32 v127, v67, v76
	v_exp_f32_e32 v66, v126
	v_exp_f32_e32 v67, v127
	v_fmac_f32_e32 v128, v68, v76
	v_fmac_f32_e32 v129, v69, v76
	v_exp_f32_e32 v68, v128
	v_exp_f32_e32 v69, v129
	v_fmac_f32_e32 v138, v70, v76
	v_fmac_f32_e32 v130, v71, v76
	v_exp_f32_e32 v70, v138
	v_exp_f32_e32 v71, v130
	v_pk_add_f32 v[66:67], v[66:67], s[0:1] op_sel_hi:[1,0]
	v_fmac_f32_e32 v123, v72, v76
	v_fmac_f32_e32 v124, v73, v76
	v_rcp_f32_e32 v66, v66
	v_exp_f32_e32 v72, v123
	v_exp_f32_e32 v73, v124
	v_pk_add_f32 v[68:69], v[68:69], s[0:1] op_sel_hi:[1,0]
	v_rcp_f32_e32 v67, v67
	v_rcp_f32_e32 v68, v68
	v_pk_add_f32 v[70:71], v[70:71], s[0:1] op_sel_hi:[1,0]
	v_max_f32_e32 v66, 1.0, v66
	v_rcp_f32_e32 v70, v70
	v_pk_add_f32 v[72:73], v[72:73], s[0:1] op_sel_hi:[1,0]
	v_cvt_pk_u8_f32 v66, v66, 0, 0
	v_rcp_f32_e32 v71, v71
	v_max_f32_e32 v67, 1.0, v67
	v_cvt_pk_u8_f32 v66, v67, 1, v66
	v_rcp_f32_e32 v67, v72
	v_max_f32_e32 v68, 1.0, v68
	v_rcp_f32_e32 v69, v69
	v_cvt_pk_u8_f32 v66, v68, 2, v66
	v_rcp_f32_e32 v68, v73
	v_max_f32_e32 v70, 1.0, v70
	v_cvt_pk_u8_f32 v70, v70, 0, 0
	v_max_f32_e32 v71, 1.0, v71
	v_cvt_pk_u8_f32 v70, v71, 1, v70
	v_max_f32_e32 v67, 1.0, v67
	v_max_f32_e32 v69, 1.0, v69
	s_mov_b32 s30, 0x1c00
	v_cvt_pk_u8_f32 v67, v67, 2, v70
	v_max_f32_e32 v68, 1.0, v68
	v_cvt_pk_u8_f32 v69, v69, 3, v66
	v_add_co_u32_e32 v66, vcc, s30, v148
	v_cvt_pk_u8_f32 v133, v133, 3, v125
	v_cvt_pk_u8_f32 v68, v68, 3, v67
	v_addc_co_u32_e32 v67, vcc, 0, v149, vcc
	global_store_dwordx2 v146, v[132:133], s[98:99]
	global_store_dwordx2 v[66:67], v[68:69], off
	global_load_dwordx4 v[70:73], v159, s[62:63] offset:528
	global_load_dwordx4 v[78:81], v159, s[62:63] offset:512
	global_load_dwordx4 v[86:89], v159, s[52:53] offset:528
	global_load_dwordx4 v[94:97], v159, s[52:53] offset:512
	s_mov_b64 s[30:31], -1
	s_andn2_b64 vcc, exec, s[38:39]
	s_waitcnt vmcnt(0)
	v_add_f32_e32 v68, v78, v94
	v_fmamk_f32 v68, v68, 0xbfb8aa3b, v236
	v_fma_f32 v62, v62, v147, v68
	v_exp_f32_e32 v78, v62
	v_add_f32_e32 v62, v70, v86
	v_fmamk_f32 v62, v62, 0xbfb8aa3b, v236
	v_fma_f32 v58, v58, v147, v62
	v_exp_f32_e32 v70, v58
	v_add_f32_e32 v58, v79, v95
	v_fmamk_f32 v58, v58, 0xbfb8aa3b, v236
	v_fma_f32 v63, v63, v147, v58
	v_exp_f32_e32 v79, v63
	v_add_f32_e32 v63, v71, v87
	v_fmamk_f32 v63, v63, 0xbfb8aa3b, v236
	v_fma_f32 v59, v59, v147, v63
	v_exp_f32_e32 v71, v59
	v_add_f32_e32 v59, v80, v96
	v_fmamk_f32 v59, v59, 0xbfb8aa3b, v236
	v_fma_f32 v64, v64, v147, v59
	v_exp_f32_e32 v80, v64
	v_add_f32_e32 v64, v72, v88
	v_fmamk_f32 v64, v64, 0xbfb8aa3b, v236
	v_fma_f32 v60, v60, v147, v64
	v_exp_f32_e32 v72, v60
	v_add_f32_e32 v60, v81, v97
	v_fmamk_f32 v60, v60, 0xbfb8aa3b, v236
	v_fma_f32 v65, v65, v147, v60
	v_exp_f32_e32 v81, v65
	v_add_f32_e32 v65, v73, v89
	v_fmamk_f32 v65, v65, 0xbfb8aa3b, v236
	v_fma_f32 v50, v50, v122, v62
	v_fma_f32 v51, v51, v122, v63
	v_fma_f32 v42, v42, v116, v62
	v_fma_f32 v43, v43, v116, v63
	v_fma_f32 v34, v34, v108, v62
	v_fma_f32 v35, v35, v108, v63
	v_fma_f32 v26, v26, v100, v62
	v_fma_f32 v27, v27, v100, v63
	v_fma_f32 v18, v18, v92, v62
	v_fma_f32 v19, v19, v92, v63
	v_fma_f32 v10, v10, v84, v62
	v_fma_f32 v11, v11, v84, v63
	v_fmac_f32_e32 v62, v2, v76
	v_fmac_f32_e32 v63, v3, v76
	v_fma_f32 v61, v61, v147, v65
	v_pk_add_f32 v[78:79], v[78:79], s[0:1] op_sel_hi:[1,0]
	v_pk_add_f32 v[70:71], v[70:71], s[0:1] op_sel_hi:[1,0]
	v_exp_f32_e32 v50, v50
	v_exp_f32_e32 v51, v51
	v_exp_f32_e32 v42, v42
	v_exp_f32_e32 v43, v43
	v_exp_f32_e32 v34, v34
	v_exp_f32_e32 v35, v35
	v_exp_f32_e32 v26, v26
	v_exp_f32_e32 v27, v27
	v_exp_f32_e32 v18, v18
	v_exp_f32_e32 v19, v19
	v_exp_f32_e32 v10, v10
	v_exp_f32_e32 v11, v11
	v_exp_f32_e32 v2, v62
	v_exp_f32_e32 v3, v63
	v_exp_f32_e32 v73, v61
	v_rcp_f32_e32 v61, v78
	v_rcp_f32_e32 v69, v70
	v_fma_f32 v52, v52, v122, v64
	v_fma_f32 v53, v53, v122, v65
	v_fma_f32 v44, v44, v116, v64
	v_fma_f32 v45, v45, v116, v65
	v_fma_f32 v36, v36, v108, v64
	v_fma_f32 v37, v37, v108, v65
	v_fma_f32 v28, v28, v100, v64
	v_fma_f32 v29, v29, v100, v65
	v_fma_f32 v20, v20, v92, v64
	v_fma_f32 v21, v21, v92, v65
	v_fma_f32 v12, v12, v84, v64
	v_fma_f32 v13, v13, v84, v65
	v_fmac_f32_e32 v64, v4, v76
	v_fmac_f32_e32 v65, v5, v76
	v_rcp_f32_e32 v70, v79
	v_rcp_f32_e32 v71, v71
	v_exp_f32_e32 v52, v52
	v_exp_f32_e32 v53, v53
	v_exp_f32_e32 v44, v44
	v_exp_f32_e32 v45, v45
	v_exp_f32_e32 v36, v36
	v_exp_f32_e32 v37, v37
	v_exp_f32_e32 v28, v28
	v_exp_f32_e32 v29, v29
	v_exp_f32_e32 v20, v20
	v_exp_f32_e32 v21, v21
	v_exp_f32_e32 v12, v12
	v_exp_f32_e32 v13, v13
	v_exp_f32_e32 v4, v64
	v_exp_f32_e32 v5, v65
	v_fma_f32 v54, v54, v122, v68
	v_fma_f32 v55, v55, v122, v58
	v_fma_f32 v46, v46, v116, v68
	v_fma_f32 v47, v47, v116, v58
	v_fma_f32 v38, v38, v108, v68
	v_fma_f32 v39, v39, v108, v58
	v_fma_f32 v30, v30, v100, v68
	v_fma_f32 v31, v31, v100, v58
	v_fma_f32 v22, v22, v92, v68
	v_fma_f32 v23, v23, v92, v58
	v_fma_f32 v14, v14, v84, v68
	v_fma_f32 v15, v15, v84, v58
	v_fmac_f32_e32 v68, v6, v76
	v_fmac_f32_e32 v58, v7, v76
	v_exp_f32_e32 v54, v54
	v_exp_f32_e32 v55, v55
	v_pk_add_f32 v[50:51], v[50:51], s[0:1] op_sel_hi:[1,0]
	v_exp_f32_e32 v46, v46
	v_exp_f32_e32 v47, v47
	v_pk_add_f32 v[42:43], v[42:43], s[0:1] op_sel_hi:[1,0]
;     template <int QVV> __device__ __forceinline__ void run(f32x4 (&acc)[2][2][4][2], const Unit& u, int wr, int wc, int fr, int fq) const {
;     ...
; #pragma unroll
;             for (int ai = 0; ai < 2; ++ai)
; #pragma unroll
;                 for (int m = 0; m < 4; ++m) { if (ai >= nai) continue;
;                     const float rn = rs[ai][m] * (-LOG2E);
;                     const f32x4 x0 = acc[ai][bj][m][0] * rn + s0, x1 = acc[ai][bj][m][1] * rn + s1;
;                     f32x4 d0, d1;
; #pragma unroll
;                     for (int i = 0; i < 4; ++i) { d0[i] = __builtin_amdgcn_exp2f(x0[i]); d1[i] = __builtin_amdgcn_exp2f(x1[i]); }
;                     d0 = d0 + (1.0f / 255.0f); d1 = d1 + (1.0f / 255.0f);
;                     u32x2 w = {0u, 0u};
; #pragma unroll
;                     for (int i = 0; i < 4; ++i) { const float g0 = fmaxf(__builtin_amdgcn_rcpf(d0[i]), 1.0f), g1 = fmaxf(__builtin_amdgcn_rcpf(d1[i]), 1.0f);
;                         w.x = __builtin_amdgcn_cvt_pk_u8_f32(g0, i, w.x); w.y = __builtin_amdgcn_cvt_pk_u8_f32(g1, i, w.y); }
;                     *(u32x2*)(tb + lo + (unsigned)((ai * HALF + m * 16) * NGC + bj * HALF)) = w; }
	v_exp_f32_e32 v38, v38
	v_exp_f32_e32 v39, v39
	v_pk_add_f32 v[34:35], v[34:35], s[0:1] op_sel_hi:[1,0]
	v_exp_f32_e32 v30, v30
	v_exp_f32_e32 v31, v31
	v_pk_add_f32 v[26:27], v[26:27], s[0:1] op_sel_hi:[1,0]
	v_exp_f32_e32 v22, v22
	v_exp_f32_e32 v23, v23
	v_pk_add_f32 v[18:19], v[18:19], s[0:1] op_sel_hi:[1,0]
	v_exp_f32_e32 v14, v14
	v_exp_f32_e32 v15, v15
	v_pk_add_f32 v[10:11], v[10:11], s[0:1] op_sel_hi:[1,0]
	v_exp_f32_e32 v6, v68
	v_exp_f32_e32 v7, v58
	v_pk_add_f32 v[2:3], v[2:3], s[0:1] op_sel_hi:[1,0]
	v_max_f32_e32 v61, 1.0, v61
	v_max_f32_e32 v69, 1.0, v69
	v_fma_f32 v56, v56, v122, v59
	v_fma_f32 v57, v57, v122, v60
	v_rcp_f32_e32 v50, v50
	v_fma_f32 v48, v48, v116, v59
	v_fma_f32 v49, v49, v116, v60
	v_rcp_f32_e32 v42, v42
	v_fma_f32 v40, v40, v108, v59
	v_fma_f32 v41, v41, v108, v60
	v_rcp_f32_e32 v34, v34
	v_fma_f32 v32, v32, v100, v59
	v_fma_f32 v33, v33, v100, v60
	v_rcp_f32_e32 v26, v26
	v_fma_f32 v24, v24, v92, v59
	v_fma_f32 v25, v25, v92, v60
	v_rcp_f32_e32 v18, v18
	v_fma_f32 v16, v16, v84, v59
	v_fma_f32 v17, v17, v84, v60
	v_rcp_f32_e32 v10, v10
	v_fmac_f32_e32 v59, v8, v76
	v_fmac_f32_e32 v60, v9, v76
	v_rcp_f32_e32 v2, v2
	v_pk_add_f32 v[80:81], v[80:81], s[0:1] op_sel_hi:[1,0]
	v_pk_add_f32 v[72:73], v[72:73], s[0:1] op_sel_hi:[1,0]
	v_cvt_pk_u8_f32 v61, v61, 0, 0
	v_cvt_pk_u8_f32 v69, v69, 0, 0
	v_max_f32_e32 v70, 1.0, v70
	v_max_f32_e32 v71, 1.0, v71
	v_exp_f32_e32 v56, v56
	v_exp_f32_e32 v57, v57
	v_pk_add_f32 v[52:53], v[52:53], s[0:1] op_sel_hi:[1,0]
	v_rcp_f32_e32 v51, v51
	v_exp_f32_e32 v48, v48
	v_exp_f32_e32 v49, v49
	v_pk_add_f32 v[44:45], v[44:45], s[0:1] op_sel_hi:[1,0]
	v_rcp_f32_e32 v43, v43
	v_exp_f32_e32 v40, v40
	v_exp_f32_e32 v41, v41
	v_pk_add_f32 v[36:37], v[36:37], s[0:1] op_sel_hi:[1,0]
	v_rcp_f32_e32 v35, v35
	v_exp_f32_e32 v32, v32
	v_exp_f32_e32 v33, v33
	v_pk_add_f32 v[28:29], v[28:29], s[0:1] op_sel_hi:[1,0]
	v_rcp_f32_e32 v27, v27
	v_exp_f32_e32 v24, v24
	v_exp_f32_e32 v25, v25
	v_pk_add_f32 v[20:21], v[20:21], s[0:1] op_sel_hi:[1,0]
	v_rcp_f32_e32 v19, v19
	v_exp_f32_e32 v16, v16
	v_exp_f32_e32 v17, v17
	v_pk_add_f32 v[12:13], v[12:13], s[0:1] op_sel_hi:[1,0]
	v_rcp_f32_e32 v11, v11
	v_exp_f32_e32 v8, v59
	v_exp_f32_e32 v9, v60
	v_pk_add_f32 v[4:5], v[4:5], s[0:1] op_sel_hi:[1,0]
	v_rcp_f32_e32 v3, v3
	v_cvt_pk_u8_f32 v61, v70, 1, v61
	v_cvt_pk_u8_f32 v69, v71, 1, v69
	v_rcp_f32_e32 v70, v80
	v_rcp_f32_e32 v71, v72
	v_rcp_f32_e32 v52, v52
	v_rcp_f32_e32 v44, v44
	v_rcp_f32_e32 v36, v36
	v_rcp_f32_e32 v28, v28
	v_rcp_f32_e32 v20, v20
	v_rcp_f32_e32 v12, v12
	v_rcp_f32_e32 v4, v4
	v_pk_add_f32 v[54:55], v[54:55], s[0:1] op_sel_hi:[1,0]
	v_pk_add_f32 v[46:47], v[46:47], s[0:1] op_sel_hi:[1,0]
	v_pk_add_f32 v[38:39], v[38:39], s[0:1] op_sel_hi:[1,0]
	v_pk_add_f32 v[30:31], v[30:31], s[0:1] op_sel_hi:[1,0]
	v_pk_add_f32 v[22:23], v[22:23], s[0:1] op_sel_hi:[1,0]
	v_pk_add_f32 v[14:15], v[14:15], s[0:1] op_sel_hi:[1,0]
	v_pk_add_f32 v[6:7], v[6:7], s[0:1] op_sel_hi:[1,0]
	v_rcp_f32_e32 v54, v54
	v_max_f32_e32 v50, 1.0, v50
	v_rcp_f32_e32 v46, v46
	v_max_f32_e32 v42, 1.0, v42
	v_rcp_f32_e32 v38, v38
	v_max_f32_e32 v34, 1.0, v34
	v_rcp_f32_e32 v30, v30
	v_max_f32_e32 v26, 1.0, v26
	v_rcp_f32_e32 v22, v22
	v_max_f32_e32 v18, 1.0, v18
	v_rcp_f32_e32 v14, v14
	v_max_f32_e32 v10, 1.0, v10
	v_rcp_f32_e32 v6, v6
	v_max_f32_e32 v2, 1.0, v2
	v_pk_add_f32 v[56:57], v[56:57], s[0:1] op_sel_hi:[1,0]
	v_cvt_pk_u8_f32 v50, v50, 0, 0
	v_rcp_f32_e32 v55, v55
	v_max_f32_e32 v51, 1.0, v51
	v_pk_add_f32 v[48:49], v[48:49], s[0:1] op_sel_hi:[1,0]
	v_cvt_pk_u8_f32 v42, v42, 0, 0
	v_rcp_f32_e32 v47, v47
	v_max_f32_e32 v43, 1.0, v43
	v_pk_add_f32 v[40:41], v[40:41], s[0:1] op_sel_hi:[1,0]
	v_cvt_pk_u8_f32 v34, v34, 0, 0
	v_rcp_f32_e32 v39, v39
	v_max_f32_e32 v35, 1.0, v35
	v_pk_add_f32 v[32:33], v[32:33], s[0:1] op_sel_hi:[1,0]
	v_cvt_pk_u8_f32 v26, v26, 0, 0
	v_rcp_f32_e32 v31, v31
	v_max_f32_e32 v27, 1.0, v27
	v_pk_add_f32 v[24:25], v[24:25], s[0:1] op_sel_hi:[1,0]
	v_cvt_pk_u8_f32 v18, v18, 0, 0
	v_rcp_f32_e32 v23, v23
	v_max_f32_e32 v19, 1.0, v19
	v_pk_add_f32 v[16:17], v[16:17], s[0:1] op_sel_hi:[1,0]
	v_cvt_pk_u8_f32 v10, v10, 0, 0
	v_rcp_f32_e32 v15, v15
	v_max_f32_e32 v11, 1.0, v11
	v_pk_add_f32 v[8:9], v[8:9], s[0:1] op_sel_hi:[1,0]
	v_cvt_pk_u8_f32 v2, v2, 0, 0
	v_rcp_f32_e32 v7, v7
;     template <int QVV> __device__ __forceinline__ void run(f32x4 (&acc)[2][2][4][2], const Unit& u, int wr, int wc, int fr, int fq) const {
;     ...
; #pragma unroll
;             for (int ai = 0; ai < 2; ++ai)
; #pragma unroll
;                 for (int m = 0; m < 4; ++m) { if (ai >= nai) continue;
;                     const float rn = rs[ai][m] * (-LOG2E);
;                     const f32x4 x0 = acc[ai][bj][m][0] * rn + s0, x1 = acc[ai][bj][m][1] * rn + s1;
;                     f32x4 d0, d1;
; #pragma unroll
;                     for (int i = 0; i < 4; ++i) { d0[i] = __builtin_amdgcn_exp2f(x0[i]); d1[i] = __builtin_amdgcn_exp2f(x1[i]); }
;                     d0 = d0 + (1.0f / 255.0f); d1 = d1 + (1.0f / 255.0f);
;                     u32x2 w = {0u, 0u};
; #pragma unroll
;                     for (int i = 0; i < 4; ++i) { const float g0 = fmaxf(__builtin_amdgcn_rcpf(d0[i]), 1.0f), g1 = fmaxf(__builtin_amdgcn_rcpf(d1[i]), 1.0f);
;                         w.x = __builtin_amdgcn_cvt_pk_u8_f32(g0, i, w.x); w.y = __builtin_amdgcn_cvt_pk_u8_f32(g1, i, w.y); }
;                     *(u32x2*)(tb + lo + (unsigned)((ai * HALF + m * 16) * NGC + bj * HALF)) = w; }
	v_max_f32_e32 v3, 1.0, v3
	v_max_f32_e32 v70, 1.0, v70
	v_max_f32_e32 v71, 1.0, v71
	v_cvt_pk_u8_f32 v50, v51, 1, v50
	v_rcp_f32_e32 v51, v56
	v_max_f32_e32 v52, 1.0, v52
	v_cvt_pk_u8_f32 v42, v43, 1, v42
	v_rcp_f32_e32 v43, v48
	v_max_f32_e32 v44, 1.0, v44
	v_cvt_pk_u8_f32 v34, v35, 1, v34
	v_rcp_f32_e32 v35, v40
	v_max_f32_e32 v36, 1.0, v36
	v_cvt_pk_u8_f32 v26, v27, 1, v26
	v_rcp_f32_e32 v27, v32
	v_max_f32_e32 v28, 1.0, v28
	v_cvt_pk_u8_f32 v18, v19, 1, v18
	v_rcp_f32_e32 v19, v24
	v_max_f32_e32 v20, 1.0, v20
	v_cvt_pk_u8_f32 v10, v11, 1, v10
	v_rcp_f32_e32 v11, v16
	v_max_f32_e32 v12, 1.0, v12
	v_cvt_pk_u8_f32 v2, v3, 1, v2
	v_rcp_f32_e32 v3, v8
	v_max_f32_e32 v4, 1.0, v4
	v_cvt_pk_u8_f32 v61, v70, 2, v61
	v_cvt_pk_u8_f32 v69, v71, 2, v69
	v_rcp_f32_e32 v70, v81
	v_rcp_f32_e32 v71, v73
	v_cvt_pk_u8_f32 v52, v52, 2, v50
	v_rcp_f32_e32 v50, v57
	v_rcp_f32_e32 v53, v53
	v_cvt_pk_u8_f32 v44, v44, 2, v42
	v_rcp_f32_e32 v42, v49
	v_rcp_f32_e32 v45, v45
	v_cvt_pk_u8_f32 v36, v36, 2, v34
	v_rcp_f32_e32 v34, v41
	v_rcp_f32_e32 v37, v37
	v_cvt_pk_u8_f32 v28, v28, 2, v26
	v_rcp_f32_e32 v26, v33
	v_rcp_f32_e32 v29, v29
	v_cvt_pk_u8_f32 v20, v20, 2, v18
	v_rcp_f32_e32 v18, v25
	v_rcp_f32_e32 v21, v21
	v_cvt_pk_u8_f32 v12, v12, 2, v10
	v_rcp_f32_e32 v10, v17
	v_rcp_f32_e32 v13, v13
	v_cvt_pk_u8_f32 v4, v4, 2, v2
	v_rcp_f32_e32 v2, v9
	v_rcp_f32_e32 v5, v5
	v_max_f32_e32 v54, 1.0, v54
	v_max_f32_e32 v46, 1.0, v46
	v_max_f32_e32 v38, 1.0, v38
	v_max_f32_e32 v30, 1.0, v30
	v_max_f32_e32 v22, 1.0, v22
	v_max_f32_e32 v14, 1.0, v14
	v_max_f32_e32 v6, 1.0, v6
	v_cvt_pk_u8_f32 v54, v54, 0, 0
	v_max_f32_e32 v55, 1.0, v55
	v_cvt_pk_u8_f32 v46, v46, 0, 0
	v_max_f32_e32 v47, 1.0, v47
	v_cvt_pk_u8_f32 v38, v38, 0, 0
	v_max_f32_e32 v39, 1.0, v39
	v_cvt_pk_u8_f32 v30, v30, 0, 0
	v_max_f32_e32 v31, 1.0, v31
	v_cvt_pk_u8_f32 v22, v22, 0, 0
	v_max_f32_e32 v23, 1.0, v23
	v_cvt_pk_u8_f32 v14, v14, 0, 0
	v_max_f32_e32 v15, 1.0, v15
	v_cvt_pk_u8_f32 v6, v6, 0, 0
	v_max_f32_e32 v7, 1.0, v7
	v_cvt_pk_u8_f32 v54, v55, 1, v54
	v_max_f32_e32 v51, 1.0, v51
	v_cvt_pk_u8_f32 v46, v47, 1, v46
	v_max_f32_e32 v43, 1.0, v43
	v_cvt_pk_u8_f32 v38, v39, 1, v38
	v_max_f32_e32 v35, 1.0, v35
	v_cvt_pk_u8_f32 v30, v31, 1, v30
	v_max_f32_e32 v27, 1.0, v27
	v_cvt_pk_u8_f32 v22, v23, 1, v22
	v_max_f32_e32 v19, 1.0, v19
	v_cvt_pk_u8_f32 v14, v15, 1, v14
	v_max_f32_e32 v11, 1.0, v11
	v_cvt_pk_u8_f32 v6, v7, 1, v6
	v_max_f32_e32 v3, 1.0, v3
	v_max_f32_e32 v70, 1.0, v70
	v_max_f32_e32 v71, 1.0, v71
	v_cvt_pk_u8_f32 v51, v51, 2, v54
	v_max_f32_e32 v50, 1.0, v50
	v_max_f32_e32 v53, 1.0, v53
	v_cvt_pk_u8_f32 v43, v43, 2, v46
	v_max_f32_e32 v42, 1.0, v42
	v_max_f32_e32 v45, 1.0, v45
	v_cvt_pk_u8_f32 v35, v35, 2, v38
	v_max_f32_e32 v34, 1.0, v34
	v_max_f32_e32 v37, 1.0, v37
	v_cvt_pk_u8_f32 v27, v27, 2, v30
	v_max_f32_e32 v26, 1.0, v26
	v_max_f32_e32 v29, 1.0, v29
	v_cvt_pk_u8_f32 v19, v19, 2, v22
	v_max_f32_e32 v18, 1.0, v18
	v_max_f32_e32 v21, 1.0, v21
	v_cvt_pk_u8_f32 v11, v11, 2, v14
	v_max_f32_e32 v10, 1.0, v10
	v_max_f32_e32 v13, 1.0, v13
	v_cvt_pk_u8_f32 v3, v3, 2, v6
	v_max_f32_e32 v2, 1.0, v2
	v_max_f32_e32 v5, 1.0, v5
	v_cvt_pk_u8_f32 v70, v70, 3, v61
	v_cvt_pk_u8_f32 v71, v71, 3, v69
	v_cvt_pk_u8_f32 v50, v50, 3, v51
	v_cvt_pk_u8_f32 v51, v53, 3, v52
	v_cvt_pk_u8_f32 v42, v42, 3, v43
	v_cvt_pk_u8_f32 v43, v45, 3, v44
	v_cvt_pk_u8_f32 v34, v34, 3, v35
	v_cvt_pk_u8_f32 v35, v37, 3, v36
	v_cvt_pk_u8_f32 v26, v26, 3, v27
	v_cvt_pk_u8_f32 v27, v29, 3, v28
	v_cvt_pk_u8_f32 v18, v18, 3, v19
	v_cvt_pk_u8_f32 v19, v21, 3, v20
	v_cvt_pk_u8_f32 v10, v10, 3, v11
	v_cvt_pk_u8_f32 v11, v13, 3, v12
	v_cvt_pk_u8_f32 v2, v2, 3, v3
	v_cvt_pk_u8_f32 v3, v5, 3, v4
	global_store_dwordx2 v146, v[70:71], s[98:99] offset:128
	global_store_dwordx2 v[114:115], v[50:51], off offset:128
	global_store_dwordx2 v[106:107], v[42:43], off offset:128
	global_store_dwordx2 v[98:99], v[34:35], off offset:128
	global_store_dwordx2 v[90:91], v[26:27], off offset:128
	global_store_dwordx2 v[82:83], v[18:19], off offset:128
	global_store_dwordx2 v[74:75], v[10:11], off offset:128
	global_store_dwordx2 v[66:67], v[2:3], off offset:128
	s_cbranch_vccnz .LBB0_1270
	s_andn2_b64 vcc, exec, s[48:49]
	v_mov_b64 v[2:3], 0
	v_mov_b64 v[4:5], 0
	s_cbranch_vccnz .LBB0_1269
	s_barrier
	s_branch .LBB0_1269

; __device__ __forceinline__ void row_rstd(const unsigned long long* ssq, int row0, float (&rs)[2][4]) {
;     ...
;     for (int ai = 0; ai < 2; ++ai)
; #pragma unroll
;         for (int m = 0; m < 4; ++m) q[ai][m] = ssq[row0 + ai * HALF + m * 16];
;     asm volatile("" : "+v"(q[0][0]), "+v"(q[0][1]), "+v"(q[0][2]), "+v"(q[0][3]), "+v"(q[1][0]), "+v"(q[1][1]), "+v"(q[1][2]), "+v"(q[1][3]));
; #pragma unroll
;     for (int ai = 0; ai < 2; ++ai)
; #pragma unroll
;         for (int m = 0; m < 4; ++m) {
;             const float qf = __builtin_fmaf((float)(unsigned)(q[ai][m] >> 32), 4294967296.0f, (float)(unsigned)q[ai][m]);
;             rs[ai][m] = __builtin_amdgcn_rsqf(__builtin_fmaf(qf, 1.0f / (SSQ_SCALE * DM), EPS)); }
;     template <int QVV> __device__ __forceinline__ void run(f32x4 (&acc)[2][2][4][2], const Unit& u, int wr, int wc, int fr, int fq) const {
;         constexpr int nai = (QVV == 2) ? 1 : 2; const int r0 = u.pm * BM + (QVV == 2 ? (u.seg - 1) * HALF : 0);
;         char* tb = (char*)(O + (size_t)r0 * NGC + u.pn * BM);
;         const int v = u.pm < 4 ? 4 : ((u.pm - 4) >> 5);
;         const char* swb = (const char*)(sw + (size_t)v * SWLD + u.pn * BM); const char* bmb = (const char*)(bm + u.pn * BM);
;         unsigned lo = (unsigned)((wr * 64 + fr) * NGC + wc * 32 + 8 * fq);
;         unsigned co = (unsigned)(wc * 32 + 8 * fq) * 4u;
;         asm volatile("" : "+v"(lo), "+v"(co));
;         float rs[2][4]; row_rstd(ssq, r0 + wr * 64 + fr, rs);
; #pragma unroll
;         for (int bj = 0; bj < 2; ++bj) {
;             const f32x4 s0 = (*(const f32x4*)(swb + co + bj * HALF * 4) + *(const f32x4*)(bmb + co + bj * HALF * 4)) * (-LOG2E) - 7.994353436858858f,
;                         s1 = (*(const f32x4*)(swb + co + bj * HALF * 4 + 16) + *(const f32x4*)(bmb + co + bj * HALF * 4 + 16)) * (-LOG2E) - 7.994353436858858f;
; #pragma unroll
;             for (int ai = 0; ai < 2; ++ai)
; #pragma unroll
;                 for (int m = 0; m < 4; ++m) { if (ai >= nai) continue;
;                     const float rn = rs[ai][m] * (-LOG2E);
;                     const f32x4 x0 = acc[ai][bj][m][0] * rn + s0, x1 = acc[ai][bj][m][1] * rn + s1;
.LBB0_1292:
	v_readlane_b32 s99, v253, 9
	s_mul_i32 s98, s10, 24
	s_add_i32 s98, s98, s11
	s_lshl_b32 s98, s98, 16
	s_lshl_b32 s99, s99, 5
	s_add_i32 s98, s98, s99
	s_add_u32 s98, s1, s98
	s_addc_u32 s99, s2, 0
	s_movk_i32 s12, 0x1800
	v_mul_lo_u32 v66, v70, s12
	s_lshl_b32 s10, s10, 8
	v_readlane_b32 s12, v253, 9
	s_or_b32 s10, s10, s12
	v_add_u32_e32 v68, s10, v70
	v_or_b32_e32 v67, s21, v71
	v_ashrrev_i32_e32 v69, 31, v68
	v_or3_b32 v66, v66, v71, s21
	v_lshlrev_b32_e32 v71, 2, v67
	v_lshl_add_u64 v[68:69], v[68:69], 3, s[44:45]
	global_load_dwordx2 v[88:89], v[68:69], off
	global_load_dwordx2 v[90:91], v[68:69], off offset:128
	global_load_dwordx2 v[92:93], v[68:69], off offset:256
	global_load_dwordx2 v[94:95], v[68:69], off offset:384
	global_load_dwordx2 v[72:73], v[68:69], off offset:1024
	global_load_dwordx2 v[74:75], v[68:69], off offset:1152
	global_load_dwordx2 v[76:77], v[68:69], off offset:1280
	s_nop 0
	global_load_dwordx2 v[68:69], v[68:69], off offset:1408
	s_mul_hi_i32 s12, s10, 0x1800
	s_mulk_i32 s10, 0x1800
	s_add_u32 s1, s1, s10
	s_addc_u32 s2, s2, s12
	s_lshl_b32 s10, s11, 8
	s_ashr_i32 s11, s10, 31
	s_add_u32 s30, s1, s10
	s_addc_u32 s31, s2, s11
	s_lshl_b64 s[12:13], s[38:39], 2
	s_add_u32 s1, s7, s12
	s_addc_u32 s2, s9, s13
	s_lshl_b64 s[10:11], s[10:11], 2
	s_add_u32 s38, s1, s10
	s_addc_u32 s39, s2, s11
	s_add_u32 s40, s3, s10
	s_addc_u32 s41, s5, s11
	s_flbit_i32_b32 s1, 0
	v_mov_b32_e32 v67, v175
	s_min_u32 s1, s1, 32
	s_sub_i32 s2, 32, s1
	s_waitcnt vmcnt(0)
	global_load_dwordx4 v[72:75], v71, s[38:39] offset:16
	global_load_dwordx4 v[76:79], v71, s[38:39]
	global_load_dwordx4 v[80:83], v71, s[40:41]
	global_load_dwordx4 v[84:87], v71, s[40:41] offset:16
	v_mov_b32_e32 v174, v89
	v_and_b32_e32 v66, 0x1c0, v0
	v_lshlrev_b32_e32 v66, 7, v66
	v_and_b32_e32 v69, 48, v0
	v_lshl_or_b32 v66, v69, 4, v66
	v_and_b32_e32 v69, 15, v0
	v_lshl_or_b32 v66, v69, 3, v66
	v_lshl_add_u64 v[68:69], s[98:99], 0, v[66:67]
	v_cvt_f32_u32_e32 v67, v88
	v_lshlrev_b64 v[88:89], s1, v[174:175]
	v_mov_b32_e32 v174, v91
	v_cvt_f32_u32_e32 v70, v90
	v_min_u32_e32 v88, 1, v88
	v_lshlrev_b64 v[90:91], s1, v[174:175]
	v_mov_b32_e32 v174, v93
	v_or_b32_e32 v93, v89, v88
	v_min_u32_e32 v90, 1, v90
	v_lshlrev_b64 v[88:89], s1, v[174:175]
	v_mov_b32_e32 v174, v95
	v_cvt_f32_u32_e32 v93, v93
	v_or_b32_e32 v95, v91, v90
	v_cvt_f32_u32_e32 v95, v95
	v_min_u32_e32 v88, 1, v88
	v_lshlrev_b64 v[90:91], s1, v[174:175]
	v_or_b32_e32 v88, v89, v88
	v_min_u32_e32 v89, 1, v90
	v_ldexp_f32 v90, v93, s2
	v_fmac_f32_e32 v67, 0x4f800000, v90
	v_ldexp_f32 v90, v95, s2
	v_fmac_f32_e32 v70, 0x4f800000, v90
	v_fmamk_f32 v67, v67, 0x30000000, v231
	v_fmamk_f32 v70, v70, 0x30000000, v231
	v_rsq_f32_e32 v67, v67
	v_rsq_f32_e32 v70, v70
	v_cvt_f32_u32_e32 v88, v88
	v_cvt_f32_u32_e32 v92, v92
	v_mul_f32_e32 v67, 0xbfb8aa3b, v67
	v_mul_f32_e32 v70, 0xbfb8aa3b, v70
	v_or_b32_e32 v89, v91, v89
	v_cvt_f32_u32_e32 v89, v89
	v_cvt_f32_u32_e32 v94, v94
	v_ldexp_f32 v88, v88, s2
	v_fmac_f32_e32 v92, 0x4f800000, v88
	v_ldexp_f32 v88, v89, s2
	v_fmamk_f32 v89, v92, 0x30000000, v231
	v_fmac_f32_e32 v94, 0x4f800000, v88
	v_rsq_f32_e32 v88, v89
	v_fmamk_f32 v89, v94, 0x30000000, v231
	v_rsq_f32_e32 v89, v89
	s_waitcnt vmcnt(1)
	v_add_f32_e32 v76, v76, v80
	s_waitcnt vmcnt(0)
	v_add_f32_e32 v72, v72, v84
	v_add_f32_e32 v77, v77, v81
	v_add_f32_e32 v73, v73, v85
	v_add_f32_e32 v74, v74, v86
	v_add_f32_e32 v75, v75, v87
	v_add_f32_e32 v78, v78, v82
	v_add_f32_e32 v79, v79, v83
	v_fmamk_f32 v76, v76, 0xbfb8aa3b, v236
	v_fmamk_f32 v72, v72, 0xbfb8aa3b, v236
	v_fmamk_f32 v77, v77, 0xbfb8aa3b, v236
	v_fmamk_f32 v73, v73, 0xbfb8aa3b, v236
	v_fmamk_f32 v74, v74, 0xbfb8aa3b, v236
	v_fmamk_f32 v75, v75, 0xbfb8aa3b, v236
	v_fmamk_f32 v78, v78, 0xbfb8aa3b, v236
	v_fmamk_f32 v79, v79, 0xbfb8aa3b, v236
	v_fma_f32 v62, v62, v67, v76
	v_fma_f32 v58, v58, v67, v72
	v_fma_f32 v63, v63, v67, v77
	v_fma_f32 v59, v59, v67, v73
	v_fma_f32 v60, v60, v67, v74
	v_fma_f32 v61, v61, v67, v75
	v_fma_f32 v81, v50, v70, v72
	v_fma_f32 v83, v51, v70, v73
	v_fma_f32 v84, v56, v70, v78
	v_fma_f32 v85, v52, v70, v74
	v_fma_f32 v86, v57, v70, v79
	v_fma_f32 v87, v53, v70, v75
	v_exp_f32_e32 v50, v62
	v_exp_f32_e32 v52, v58
	v_exp_f32_e32 v51, v63
	v_exp_f32_e32 v53, v59
	v_exp_f32_e32 v56, v60
	v_exp_f32_e32 v57, v61
	v_exp_f32_e32 v60, v81
	v_exp_f32_e32 v61, v83
	v_pk_add_f32 v[50:51], v[50:51], s[0:1] op_sel_hi:[1,0]
	v_pk_add_f32 v[52:53], v[52:53], s[0:1] op_sel_hi:[1,0]
	v_rcp_f32_e32 v50, v50
	v_pk_add_f32 v[60:61], v[60:61], s[0:1] op_sel_hi:[1,0]
	v_rcp_f32_e32 v52, v52
	v_rcp_f32_e32 v60, v60
	v_rcp_f32_e32 v51, v51
	v_rcp_f32_e32 v53, v53
	v_rcp_f32_e32 v61, v61
	v_max_f32_e32 v50, 1.0, v50
	v_max_f32_e32 v52, 1.0, v52
	v_max_f32_e32 v60, 1.0, v60
	v_max_f32_e32 v51, 1.0, v51
	v_max_f32_e32 v53, 1.0, v53
	v_max_f32_e32 v61, 1.0, v61
	v_cvt_pk_u8_f32 v50, v50, 0, 0
	v_cvt_pk_u8_f32 v52, v52, 0, 0
	v_cvt_pk_u8_f32 v60, v60, 0, 0
	v_fma_f32 v64, v64, v67, v78
	v_fma_f32 v65, v65, v67, v79
	v_fma_f32 v80, v54, v70, v76
	v_fma_f32 v82, v55, v70, v77
	v_cvt_pk_u8_f32 v50, v51, 1, v50
	v_cvt_pk_u8_f32 v51, v53, 1, v52
	v_cvt_pk_u8_f32 v53, v61, 1, v60
	v_mul_f32_e32 v60, 0xbfb8aa3b, v88
	v_exp_f32_e32 v54, v64
	v_exp_f32_e32 v55, v65
	v_exp_f32_e32 v58, v80
	v_exp_f32_e32 v59, v82
	v_exp_f32_e32 v62, v84
	v_exp_f32_e32 v64, v85
	v_exp_f32_e32 v63, v86
	v_exp_f32_e32 v65, v87
	v_fma_f32 v42, v42, v60, v72
	v_fma_f32 v43, v43, v60, v73
	v_exp_f32_e32 v42, v42
	v_exp_f32_e32 v43, v43
	v_fma_f32 v48, v48, v60, v78
	v_fma_f32 v49, v49, v60, v79
	v_exp_f32_e32 v48, v48
	v_exp_f32_e32 v49, v49
;     template <int QVV> __device__ __forceinline__ void run(f32x4 (&acc)[2][2][4][2], const Unit& u, int wr, int wc, int fr, int fq) const {
;     ...
; #pragma unroll
;             for (int ai = 0; ai < 2; ++ai)
; #pragma unroll
;                 for (int m = 0; m < 4; ++m) { if (ai >= nai) continue;
;                     const float rn = rs[ai][m] * (-LOG2E);
;                     const f32x4 x0 = acc[ai][bj][m][0] * rn + s0, x1 = acc[ai][bj][m][1] * rn + s1;
;                     f32x4 d0, d1;
; #pragma unroll
;                     for (int i = 0; i < 4; ++i) { d0[i] = __builtin_amdgcn_exp2f(x0[i]); d1[i] = __builtin_amdgcn_exp2f(x1[i]); }
;                     d0 = d0 + (1.0f / 255.0f); d1 = d1 + (1.0f / 255.0f);
;                     u32x2 w = {0u, 0u};
; #pragma unroll
;                     for (int i = 0; i < 4; ++i) { const float g0 = fmaxf(__builtin_amdgcn_rcpf(d0[i]), 1.0f), g1 = fmaxf(__builtin_amdgcn_rcpf(d1[i]), 1.0f);
;                         w.x = __builtin_amdgcn_cvt_pk_u8_f32(g0, i, w.x); w.y = __builtin_amdgcn_cvt_pk_u8_f32(g1, i, w.y); }
;                     *(u32x2*)(tb + lo + (unsigned)((ai * HALF + m * 16) * NGC + bj * HALF)) = w; }
	v_pk_add_f32 v[54:55], v[54:55], s[0:1] op_sel_hi:[1,0]
	v_pk_add_f32 v[56:57], v[56:57], s[0:1] op_sel_hi:[1,0]
	v_pk_add_f32 v[62:63], v[62:63], s[0:1] op_sel_hi:[1,0]
	v_pk_add_f32 v[58:59], v[58:59], s[0:1] op_sel_hi:[1,0]
	v_pk_add_f32 v[64:65], v[64:65], s[0:1] op_sel_hi:[1,0]
	s_mov_b32 s1, 0x400
	v_rcp_f32_e32 v54, v54
	v_rcp_f32_e32 v56, v56
	v_pk_add_f32 v[42:43], v[42:43], s[0:1] op_sel_hi:[1,0]
	v_rcp_f32_e32 v55, v55
	v_rcp_f32_e32 v57, v57
	v_rcp_f32_e32 v42, v42
	v_pk_add_f32 v[48:49], v[48:49], s[0:1] op_sel_hi:[1,0]
	v_rcp_f32_e32 v43, v43
	v_rcp_f32_e32 v48, v48
	v_max_f32_e32 v54, 1.0, v54
	v_max_f32_e32 v56, 1.0, v56
	v_max_f32_e32 v55, 1.0, v55
	v_max_f32_e32 v57, 1.0, v57
	v_cvt_pk_u8_f32 v50, v54, 2, v50
	v_cvt_pk_u8_f32 v51, v56, 2, v51
	v_max_f32_e32 v42, 1.0, v42
	v_rcp_f32_e32 v64, v64
	v_cvt_pk_u8_f32 v50, v55, 3, v50
	v_cvt_pk_u8_f32 v51, v57, 3, v51
	v_fma_f32 v46, v46, v60, v76
	v_fma_f32 v47, v47, v60, v77
	v_cvt_pk_u8_f32 v42, v42, 0, 0
	v_max_f32_e32 v43, 1.0, v43
	global_store_dwordx2 v66, v[50:51], s[98:99]
	v_rcp_f32_e32 v50, v65
	v_exp_f32_e32 v46, v46
	v_exp_f32_e32 v47, v47
	v_fma_f32 v44, v44, v60, v74
	v_fma_f32 v45, v45, v60, v75
	v_cvt_pk_u8_f32 v42, v43, 1, v42
	v_max_f32_e32 v43, 1.0, v48
	v_mul_f32_e32 v48, 0xbfb8aa3b, v89
	v_exp_f32_e32 v44, v44
	v_exp_f32_e32 v45, v45
	v_fmac_f32_e32 v76, v38, v48
	v_fmac_f32_e32 v77, v39, v48
	v_exp_f32_e32 v38, v76
	v_exp_f32_e32 v39, v77
	v_max_f32_e32 v64, 1.0, v64
	v_fmac_f32_e32 v72, v34, v48
	v_fmac_f32_e32 v73, v35, v48
	v_cvt_pk_u8_f32 v53, v64, 2, v53
	v_max_f32_e32 v50, 1.0, v50
	v_pk_add_f32 v[46:47], v[46:47], s[0:1] op_sel_hi:[1,0]
	v_exp_f32_e32 v34, v72
	v_exp_f32_e32 v35, v73
	v_cvt_pk_u8_f32 v53, v50, 3, v53
	v_add_co_u32_e32 v50, vcc, s1, v68
	v_rcp_f32_e32 v46, v46
	v_pk_add_f32 v[44:45], v[44:45], s[0:1] op_sel_hi:[1,0]
	s_mov_b32 s1, 0x800
	v_fmac_f32_e32 v74, v36, v48
	v_fmac_f32_e32 v75, v37, v48
	v_rcp_f32_e32 v58, v58
	v_rcp_f32_e32 v47, v47
	v_fmac_f32_e32 v78, v40, v48
	v_exp_f32_e32 v36, v74
	v_fmac_f32_e32 v79, v41, v48
	v_exp_f32_e32 v37, v75
	v_pk_add_f32 v[38:39], v[38:39], s[0:1] op_sel_hi:[1,0]
	v_rcp_f32_e32 v59, v59
	v_exp_f32_e32 v40, v78
	v_exp_f32_e32 v41, v79
	v_rcp_f32_e32 v38, v38
	v_rcp_f32_e32 v62, v62
	v_pk_add_f32 v[34:35], v[34:35], s[0:1] op_sel_hi:[1,0]
	v_rcp_f32_e32 v39, v39
	v_rcp_f32_e32 v63, v63
	v_max_f32_e32 v46, 1.0, v46
	v_rcp_f32_e32 v44, v44
	v_rcp_f32_e32 v34, v34
	v_max_f32_e32 v58, 1.0, v58
	v_cvt_pk_u8_f32 v46, v46, 0, 0
	v_max_f32_e32 v47, 1.0, v47
	v_rcp_f32_e32 v45, v45
	v_pk_add_f32 v[36:37], v[36:37], s[0:1] op_sel_hi:[1,0]
	v_rcp_f32_e32 v35, v35
	v_max_f32_e32 v59, 1.0, v59
	v_cvt_pk_u8_f32 v58, v58, 0, 0
	v_cvt_pk_u8_f32 v46, v47, 1, v46
	v_rcp_f32_e32 v47, v49
	v_pk_add_f32 v[40:41], v[40:41], s[0:1] op_sel_hi:[1,0]
	v_max_f32_e32 v38, 1.0, v38
	v_rcp_f32_e32 v36, v36
	v_max_f32_e32 v62, 1.0, v62
	v_cvt_pk_u8_f32 v52, v59, 1, v58
	v_cvt_pk_u8_f32 v38, v38, 0, 0
	v_max_f32_e32 v39, 1.0, v39
	v_rcp_f32_e32 v40, v40
	v_rcp_f32_e32 v37, v37
	v_cvt_pk_u8_f32 v51, v62, 2, v52
	v_max_f32_e32 v52, 1.0, v63
	v_max_f32_e32 v44, 1.0, v44
	v_max_f32_e32 v34, 1.0, v34
	v_cvt_pk_u8_f32 v38, v39, 1, v38
	v_rcp_f32_e32 v39, v41
	v_cvt_pk_u8_f32 v52, v52, 3, v51
	v_addc_co_u32_e32 v51, vcc, 0, v69, vcc
	v_cvt_pk_u8_f32 v42, v44, 2, v42
	v_max_f32_e32 v45, 1.0, v45
	v_cvt_pk_u8_f32 v34, v34, 0, 0
	v_max_f32_e32 v35, 1.0, v35
	v_cvt_pk_u8_f32 v43, v43, 2, v46
	v_max_f32_e32 v44, 1.0, v47
	v_cvt_pk_u8_f32 v45, v45, 3, v42
	v_add_co_u32_e32 v42, vcc, s1, v68
	v_cvt_pk_u8_f32 v34, v35, 1, v34
	v_max_f32_e32 v36, 1.0, v36
	v_cvt_pk_u8_f32 v44, v44, 3, v43
	v_addc_co_u32_e32 v43, vcc, 0, v69, vcc
	v_max_f32_e32 v35, 1.0, v40
	v_cvt_pk_u8_f32 v34, v36, 2, v34
	v_max_f32_e32 v37, 1.0, v37
	s_mov_b32 s1, 0xc00
	v_cvt_pk_u8_f32 v35, v35, 2, v38
	v_max_f32_e32 v36, 1.0, v39
	v_cvt_pk_u8_f32 v37, v37, 3, v34
	v_add_co_u32_e32 v34, vcc, s1, v68
	v_cvt_pk_u8_f32 v36, v36, 3, v35
	s_nop 0
	v_addc_co_u32_e32 v35, vcc, 0, v69, vcc
	global_store_dwordx2 v[50:51], v[52:53], off
	global_store_dwordx2 v[42:43], v[44:45], off
	global_store_dwordx2 v[34:35], v[36:37], off
	global_load_dwordx4 v[36:39], v71, s[40:41] offset:512
	s_nop 0
	global_load_dwordx4 v[44:47], v71, s[38:39] offset:512
	global_load_dwordx4 v[52:55], v71, s[38:39] offset:528
	global_load_dwordx4 v[56:59], v71, s[40:41] offset:528
	s_waitcnt vmcnt(2)
	v_add_f32_e32 v36, v44, v36
	v_add_f32_e32 v37, v45, v37
	v_fmamk_f32 v36, v36, 0xbfb8aa3b, v236
	v_fmamk_f32 v37, v37, 0xbfb8aa3b, v236
	v_fma_f32 v30, v30, v67, v36
	v_fma_f32 v31, v31, v67, v37
	v_fma_f32 v22, v22, v70, v36
	v_fma_f32 v23, v23, v70, v37
	v_fma_f32 v14, v14, v60, v36
	v_fma_f32 v15, v15, v60, v37
	v_fmac_f32_e32 v36, v6, v48
	v_fmac_f32_e32 v37, v7, v48
	v_exp_f32_e32 v30, v30
	s_waitcnt vmcnt(0)
;     template <int QVV> __device__ __forceinline__ void run(f32x4 (&acc)[2][2][4][2], const Unit& u, int wr, int wc, int fr, int fq) const {
;     ...
; #pragma unroll
;             for (int ai = 0; ai < 2; ++ai)
; #pragma unroll
;                 for (int m = 0; m < 4; ++m) { if (ai >= nai) continue;
;                     const float rn = rs[ai][m] * (-LOG2E);
;                     const f32x4 x0 = acc[ai][bj][m][0] * rn + s0, x1 = acc[ai][bj][m][1] * rn + s1;
;                     f32x4 d0, d1;
; #pragma unroll
;                     for (int i = 0; i < 4; ++i) { d0[i] = __builtin_amdgcn_exp2f(x0[i]); d1[i] = __builtin_amdgcn_exp2f(x1[i]); }
;                     d0 = d0 + (1.0f / 255.0f); d1 = d1 + (1.0f / 255.0f);
;                     u32x2 w = {0u, 0u};
; #pragma unroll
;                     for (int i = 0; i < 4; ++i) { const float g0 = fmaxf(__builtin_amdgcn_rcpf(d0[i]), 1.0f), g1 = fmaxf(__builtin_amdgcn_rcpf(d1[i]), 1.0f);
;                         w.x = __builtin_amdgcn_cvt_pk_u8_f32(g0, i, w.x); w.y = __builtin_amdgcn_cvt_pk_u8_f32(g1, i, w.y); }
;                     *(u32x2*)(tb + lo + (unsigned)((ai * HALF + m * 16) * NGC + bj * HALF)) = w; }
	v_add_f32_e32 v40, v52, v56
	v_exp_f32_e32 v31, v31
	v_add_f32_e32 v41, v53, v57
	v_exp_f32_e32 v22, v22
	v_exp_f32_e32 v23, v23
	v_exp_f32_e32 v14, v14
	v_exp_f32_e32 v15, v15
	v_exp_f32_e32 v6, v36
	v_exp_f32_e32 v7, v37
	v_fmamk_f32 v40, v40, 0xbfb8aa3b, v236
	v_fmamk_f32 v41, v41, 0xbfb8aa3b, v236
	v_fma_f32 v26, v26, v67, v40
	v_fma_f32 v27, v27, v67, v41
	v_add_f32_e32 v38, v46, v38
	v_add_f32_e32 v44, v54, v58
	v_add_f32_e32 v39, v47, v39
	v_add_f32_e32 v45, v55, v59
	v_fma_f32 v18, v18, v70, v40
	v_fma_f32 v19, v19, v70, v41
	v_fma_f32 v10, v10, v60, v40
	v_fma_f32 v11, v11, v60, v41
	v_fmac_f32_e32 v40, v2, v48
	v_fmac_f32_e32 v41, v3, v48
	v_exp_f32_e32 v26, v26
	v_exp_f32_e32 v27, v27
	v_fmamk_f32 v38, v38, 0xbfb8aa3b, v236
	v_fmamk_f32 v44, v44, 0xbfb8aa3b, v236
	v_fmamk_f32 v39, v39, 0xbfb8aa3b, v236
	v_fmamk_f32 v45, v45, 0xbfb8aa3b, v236
	v_exp_f32_e32 v18, v18
	v_exp_f32_e32 v19, v19
	v_exp_f32_e32 v10, v10
	v_exp_f32_e32 v11, v11
	v_exp_f32_e32 v2, v40
	v_exp_f32_e32 v3, v41
	v_fma_f32 v32, v32, v67, v38
	v_fma_f32 v28, v28, v67, v44
	v_fma_f32 v33, v33, v67, v39
	v_fma_f32 v29, v29, v67, v45
	v_pk_add_f32 v[30:31], v[30:31], s[0:1] op_sel_hi:[1,0]
	v_fma_f32 v24, v24, v70, v38
	v_fma_f32 v20, v20, v70, v44
	v_fma_f32 v25, v25, v70, v39
	v_fma_f32 v21, v21, v70, v45
	v_pk_add_f32 v[22:23], v[22:23], s[0:1] op_sel_hi:[1,0]
	v_fma_f32 v16, v16, v60, v38
	v_fma_f32 v12, v12, v60, v44
	v_fma_f32 v17, v17, v60, v39
	v_fma_f32 v13, v13, v60, v45
	v_pk_add_f32 v[14:15], v[14:15], s[0:1] op_sel_hi:[1,0]
	v_fmac_f32_e32 v38, v8, v48
	v_fmac_f32_e32 v44, v4, v48
	v_fmac_f32_e32 v39, v9, v48
	v_fmac_f32_e32 v45, v5, v48
	v_pk_add_f32 v[6:7], v[6:7], s[0:1] op_sel_hi:[1,0]
	v_exp_f32_e32 v32, v32
	v_exp_f32_e32 v28, v28
	v_exp_f32_e32 v33, v33
	v_exp_f32_e32 v29, v29
	v_rcp_f32_e32 v30, v30
	v_exp_f32_e32 v24, v24
	v_exp_f32_e32 v20, v20
	v_exp_f32_e32 v25, v25
	v_exp_f32_e32 v21, v21
	v_rcp_f32_e32 v22, v22
	v_exp_f32_e32 v16, v16
	v_exp_f32_e32 v12, v12
	v_exp_f32_e32 v17, v17
	v_exp_f32_e32 v13, v13
	v_rcp_f32_e32 v14, v14
	v_exp_f32_e32 v8, v38
	v_exp_f32_e32 v4, v44
	v_exp_f32_e32 v9, v39
	v_exp_f32_e32 v5, v45
	v_rcp_f32_e32 v6, v6
	v_rcp_f32_e32 v31, v31
	v_rcp_f32_e32 v23, v23
	v_rcp_f32_e32 v15, v15
	v_rcp_f32_e32 v7, v7
	v_pk_add_f32 v[26:27], v[26:27], s[0:1] op_sel_hi:[1,0]
	v_pk_add_f32 v[18:19], v[18:19], s[0:1] op_sel_hi:[1,0]
	v_pk_add_f32 v[10:11], v[10:11], s[0:1] op_sel_hi:[1,0]
	v_pk_add_f32 v[2:3], v[2:3], s[0:1] op_sel_hi:[1,0]
	v_rcp_f32_e32 v26, v26
	v_rcp_f32_e32 v18, v18
	v_rcp_f32_e32 v10, v10
	v_rcp_f32_e32 v2, v2
	v_pk_add_f32 v[32:33], v[32:33], s[0:1] op_sel_hi:[1,0]
	v_pk_add_f32 v[28:29], v[28:29], s[0:1] op_sel_hi:[1,0]
	v_max_f32_e32 v30, 1.0, v30
	v_rcp_f32_e32 v27, v27
	v_pk_add_f32 v[24:25], v[24:25], s[0:1] op_sel_hi:[1,0]
	v_pk_add_f32 v[20:21], v[20:21], s[0:1] op_sel_hi:[1,0]
	v_max_f32_e32 v22, 1.0, v22
	v_rcp_f32_e32 v19, v19
	v_pk_add_f32 v[16:17], v[16:17], s[0:1] op_sel_hi:[1,0]
	v_pk_add_f32 v[12:13], v[12:13], s[0:1] op_sel_hi:[1,0]
	v_max_f32_e32 v14, 1.0, v14
	v_rcp_f32_e32 v11, v11
	v_pk_add_f32 v[8:9], v[8:9], s[0:1] op_sel_hi:[1,0]
	v_pk_add_f32 v[4:5], v[4:5], s[0:1] op_sel_hi:[1,0]
	v_max_f32_e32 v6, 1.0, v6
	v_rcp_f32_e32 v3, v3
	v_cvt_pk_u8_f32 v30, v30, 0, 0
	v_max_f32_e32 v31, 1.0, v31
	v_rcp_f32_e32 v32, v32
	v_rcp_f32_e32 v28, v28
	v_cvt_pk_u8_f32 v22, v22, 0, 0
	v_max_f32_e32 v23, 1.0, v23
	v_rcp_f32_e32 v24, v24
	v_rcp_f32_e32 v20, v20
	v_cvt_pk_u8_f32 v14, v14, 0, 0
	v_max_f32_e32 v15, 1.0, v15
	v_rcp_f32_e32 v16, v16
	v_rcp_f32_e32 v12, v12
	v_cvt_pk_u8_f32 v6, v6, 0, 0
	v_max_f32_e32 v7, 1.0, v7
	v_rcp_f32_e32 v8, v8
	v_rcp_f32_e32 v4, v4
	v_cvt_pk_u8_f32 v30, v31, 1, v30
	v_rcp_f32_e32 v31, v33
	v_rcp_f32_e32 v29, v29
	v_cvt_pk_u8_f32 v22, v23, 1, v22
	v_rcp_f32_e32 v23, v25
	v_rcp_f32_e32 v21, v21
	v_cvt_pk_u8_f32 v14, v15, 1, v14
	v_rcp_f32_e32 v15, v17
	v_rcp_f32_e32 v13, v13
	v_cvt_pk_u8_f32 v6, v7, 1, v6
	v_rcp_f32_e32 v7, v9
	v_rcp_f32_e32 v5, v5
	v_max_f32_e32 v26, 1.0, v26
	v_max_f32_e32 v18, 1.0, v18
	v_max_f32_e32 v10, 1.0, v10
	v_max_f32_e32 v2, 1.0, v2
	v_cvt_pk_u8_f32 v26, v26, 0, 0
	v_max_f32_e32 v27, 1.0, v27
	v_cvt_pk_u8_f32 v18, v18, 0, 0
	v_max_f32_e32 v19, 1.0, v19
	v_cvt_pk_u8_f32 v10, v10, 0, 0
	v_max_f32_e32 v11, 1.0, v11
	v_cvt_pk_u8_f32 v2, v2, 0, 0
	v_max_f32_e32 v3, 1.0, v3
	v_cvt_pk_u8_f32 v26, v27, 1, v26
	v_max_f32_e32 v27, 1.0, v32
	v_max_f32_e32 v28, 1.0, v28
	v_cvt_pk_u8_f32 v18, v19, 1, v18
	v_max_f32_e32 v19, 1.0, v24
	v_max_f32_e32 v20, 1.0, v20
	v_cvt_pk_u8_f32 v10, v11, 1, v10
	v_max_f32_e32 v11, 1.0, v16
	v_max_f32_e32 v12, 1.0, v12
	v_cvt_pk_u8_f32 v2, v3, 1, v2
	v_max_f32_e32 v3, 1.0, v8
	v_max_f32_e32 v4, 1.0, v4
	v_cvt_pk_u8_f32 v27, v27, 2, v30
	v_cvt_pk_u8_f32 v28, v28, 2, v26
	v_max_f32_e32 v26, 1.0, v31
	v_max_f32_e32 v29, 1.0, v29
	v_cvt_pk_u8_f32 v19, v19, 2, v22
	v_cvt_pk_u8_f32 v20, v20, 2, v18
	v_max_f32_e32 v18, 1.0, v23
	v_max_f32_e32 v21, 1.0, v21
	v_cvt_pk_u8_f32 v11, v11, 2, v14
	v_cvt_pk_u8_f32 v12, v12, 2, v10
	v_max_f32_e32 v10, 1.0, v15
	v_max_f32_e32 v13, 1.0, v13
	v_cvt_pk_u8_f32 v3, v3, 2, v6
	v_cvt_pk_u8_f32 v4, v4, 2, v2
	v_max_f32_e32 v2, 1.0, v7
	v_max_f32_e32 v5, 1.0, v5
	v_cvt_pk_u8_f32 v26, v26, 3, v27
	v_cvt_pk_u8_f32 v27, v29, 3, v28
	v_cvt_pk_u8_f32 v18, v18, 3, v19
	v_cvt_pk_u8_f32 v19, v21, 3, v20
	v_cvt_pk_u8_f32 v10, v10, 3, v11
	v_cvt_pk_u8_f32 v11, v13, 3, v12
	v_cvt_pk_u8_f32 v2, v2, 3, v3
	v_cvt_pk_u8_f32 v3, v5, 3, v4
	global_store_dwordx2 v66, v[26:27], s[98:99] offset:128
	global_store_dwordx2 v[50:51], v[18:19], off offset:128
	global_store_dwordx2 v[42:43], v[10:11], off offset:128
	global_store_dwordx2 v[34:35], v[2:3], off offset:128
	s_waitcnt vmcnt(0)
	s_barrier

;     template <int QVV> __device__ __forceinline__ void run(f32x4 (&acc)[2][2][4][2], const Unit& u, int wr, int wc, int fr, int fq) const {
;         const int s = u.seg & 3, s1 = s < 2 ? s + 1 : s, hh = u.seg >> 2, r0 = u.pm * BM + (QVV == 2 ? (hh - 1) * HALF : 0); constexpr int nai = (QVV == 2) ? 1 : 2;
;         const char* g0b = (const char*)(G + (size_t)r0 * NGC + s * DM + u.pn * BM); const char* g1b = (const char*)(G + (size_t)r0 * NGC + s1 * DM + u.pn * BM);
;         char* ob = (char*)(O + (size_t)r0 * DM + u.pn * BM);
;         unsigned co = (unsigned)(wc * 32 + 8 * fq);
;         asm volatile("" : "+v"(co));
;         unsigned lg = (unsigned)((wr * 64 + fr) * NGC) + co, lw = ((unsigned)((wr * 64 + fr) * DM) + co) * 2u;
;         asm volatile("" : "+v"(lg), "+v"(lw));
;         const bool last = (s == 2);
;         const unsigned lm = last ? 0xffffffffu : 0u;
; #pragma unroll
;         for (int bj = 0; bj < 2; ++bj) {
;             u32x2 g0v[2][4], g1v[2][4];
; #pragma unroll
;             for (int ai = 0; ai < 2; ++ai)
; #pragma unroll
;                 for (int m = 0; m < 4; ++m) { if (ai >= nai) continue; const unsigned rr = (unsigned)(ai * HALF + m * 16);
;                     g0v[ai][m] = *(const u32x2*)(g0b + lg + rr * NGC + bj * HALF); g1v[ai][m] = *(const u32x2*)(g1b + lg + rr * NGC + bj * HALF); }
; #pragma unroll
;             for (int ai = 0; ai < 2; ++ai)
; #pragma unroll
;                 for (int m = 0; m < 4; ++m) { if (ai >= nai) continue; const unsigned rr = (unsigned)(ai * HALF + m * 16);
;                     float o[8];
; #pragma unroll
;                     for (int n = 0; n < 2; ++n)
; #pragma unroll
;                         for (int i = 0; i < 4; ++i) {
;                             const unsigned w0 = n == 0 ? g0v[ai][m].x : g0v[ai][m].y, w1 = (n == 0 ? g1v[ai][m].x : g1v[ai][m].y) | lm;
;                             const float q0 = (float)((w0 >> (8 * i)) & 255u), q1 = (float)((w1 >> (8 * i)) & 255u);
;                             const float f = q0 * __builtin_amdgcn_rcpf(q1);
;                             const float v = acc[ai][bj][m][n][i] * f; acc[ai][bj][m][n][i] = v; o[n * 4 + i] = v; }
;                     if (last) { u32x4 w; w.x = pk2(o[0], o[1]); w.y = pk2(o[2], o[3]); w.z = pk2(o[4], o[5]); w.w = pk2(o[6], o[7]);
;                         *(u32x4*)(ob + lw + (rr * DM + bj * HALF) * 2u) = w; } }
.LBB0_1380:
	s_and_b32 s30, s42, 3
	s_cmp_lt_u32 s30, 2
	s_cselect_b32 s31, 1, 0
	s_add_i32 s31, s30, s31
	s_mul_i32 s98, s41, 24
	s_add_i32 s98, s98, s40
	s_lshl_b32 s30, s30, 3
	s_lshl_b32 s31, s31, 3
	s_add_i32 s99, s98, s31
	s_add_i32 s98, s98, s30
	s_lshl_b32 s98, s98, 16
	s_lshl_b32 s99, s99, 16
	s_and_b32 s59, s42, 3
	s_cmp_lt_u32 s59, 2
	s_cselect_b64 s[30:31], -1, 0
	s_cmp_lg_u64 s[30:31], 0
	s_addc_u32 s50, s59, 0
	s_lshl_b32 s30, s41, 8
	s_ashr_i32 s31, s30, 31
	s_mul_i32 s41, s41, 0x180000
	s_mul_hi_i32 s42, s30, 0x1800
	s_add_u32 s51, s9, s41
	s_addc_u32 s60, s10, s42
	s_lshl_b32 s41, s59, 11
	s_add_u32 s42, s51, s41
	s_addc_u32 s43, s60, 0
	s_lshl_b32 s40, s40, 8
	s_ashr_i32 s41, s40, 31
	s_add_u32 s42, s42, s40
	s_addc_u32 s43, s43, s41
	s_lshl_b32 s50, s50, 11
	v_mov_b32_e32 v130, v182
	s_add_u32 s50, s51, s50
	s_addc_u32 s51, s60, 0
	v_and_b32_e32 v174, 0x1c0, v0
	v_lshlrev_b32_e32 v174, 7, v174
	v_and_b32_e32 v132, 48, v0
	v_lshl_or_b32 v174, v132, 4, v174
	v_and_b32_e32 v132, 15, v0
	v_lshl_or_b32 v174, v132, 3, v174
	v_lshl_add_u32 v130, v130, 1, v184
	s_add_u32 s50, s50, s40
	s_addc_u32 s51, s51, s41
	s_add_u32 s42, s9, s98
	s_addc_u32 s43, s10, 0
	s_add_u32 s50, s9, s99
	s_addc_u32 s51, s10, 0
	global_load_dwordx2 v[180:181], v174, s[42:43]
	global_load_dwordx2 v[190:191], v174, s[50:51]
	v_lshl_add_u64 v[134:135], s[42:43], 0, v[174:175]
	s_mov_b32 s42, 0x400
	v_add_co_u32_e32 v136, vcc, s42, v134
	v_lshl_add_u64 v[132:133], s[50:51], 0, v[174:175]
	s_nop 0
	v_addc_co_u32_e32 v137, vcc, 0, v135, vcc
	v_add_co_u32_e32 v138, vcc, s42, v132
	s_mov_b32 s42, 0x800
	s_nop 0
	v_addc_co_u32_e32 v139, vcc, 0, v133, vcc
	v_add_co_u32_e32 v140, vcc, s42, v134
	s_lshl_b64 s[30:31], s[30:31], 12
	s_nop 0
	v_addc_co_u32_e32 v141, vcc, 0, v135, vcc
	v_add_co_u32_e32 v142, vcc, s42, v132
	s_mov_b32 s42, 0xc00
	s_nop 0
	v_addc_co_u32_e32 v143, vcc, 0, v133, vcc
	global_load_dwordx2 v[168:169], v[136:137], off
	global_load_dwordx2 v[170:171], v[138:139], off
	global_load_dwordx2 v[164:165], v[140:141], off
	global_load_dwordx2 v[166:167], v[142:143], off
	v_add_co_u32_e32 v136, vcc, s42, v134
	v_mov_b32_e32 v131, v175
	s_nop 0
	v_addc_co_u32_e32 v137, vcc, 0, v135, vcc
	v_add_co_u32_e32 v138, vcc, s42, v132
	s_mov_b32 s42, 0x1000
	s_nop 0
	v_addc_co_u32_e32 v139, vcc, 0, v133, vcc
	v_add_co_u32_e32 v140, vcc, s42, v134
	s_waitcnt vmcnt(5)
	v_cvt_f32_ubyte1_e32 v195, v180
	v_addc_co_u32_e32 v141, vcc, 0, v135, vcc
	v_add_co_u32_e32 v142, vcc, s42, v132
	s_mov_b32 s42, 0x1400
	s_nop 0
	v_addc_co_u32_e32 v143, vcc, 0, v133, vcc
	v_add_co_u32_e32 v144, vcc, s42, v134
	v_cvt_f32_ubyte0_e32 v194, v180
	s_nop 0
	v_addc_co_u32_e32 v145, vcc, 0, v135, vcc
	v_add_co_u32_e32 v146, vcc, s42, v132
	s_mov_b32 s42, 0x1800
	s_nop 0
	v_addc_co_u32_e32 v147, vcc, 0, v133, vcc
	global_load_dwordx2 v[160:161], v[136:137], off
	global_load_dwordx2 v[162:163], v[138:139], off
	global_load_dwordx2 v[152:153], v[144:145], off
	global_load_dwordx2 v[154:155], v[146:147], off
	v_add_co_u32_e32 v136, vcc, s42, v134
	s_nop 1
	v_addc_co_u32_e32 v137, vcc, 0, v135, vcc
	v_add_co_u32_e32 v138, vcc, s42, v132
	s_mov_b32 s42, 0x1c00
	s_nop 0
	v_addc_co_u32_e32 v139, vcc, 0, v133, vcc
	global_load_dwordx2 v[156:157], v[140:141], off
	global_load_dwordx2 v[158:159], v[142:143], off
	global_load_dwordx2 v[148:149], v[136:137], off
	global_load_dwordx2 v[150:151], v[138:139], off
	v_add_co_u32_e32 v136, vcc, s42, v134
	s_nop 1
	v_addc_co_u32_e32 v137, vcc, 0, v135, vcc
	v_add_co_u32_e32 v138, vcc, s42, v132
	s_add_u32 s42, s44, s30
	s_nop 0
	v_addc_co_u32_e32 v139, vcc, 0, v133, vcc
	global_load_dwordx2 v[144:145], v[136:137], off
	global_load_dwordx2 v[146:147], v[138:139], off
	s_addc_u32 s43, s45, s31
	s_lshl_b64 s[30:31], s[40:41], 1
	s_add_u32 s30, s42, s30
	s_addc_u32 s31, s43, s31
	s_cmp_eq_u32 s59, 2
	s_cselect_b64 s[40:41], -1, 0
	s_waitcnt vmcnt(14)
	v_cndmask_b32_e64 v174, v190, v248, s[40:41]
	v_cvt_f32_ubyte0_e32 v174, v174
	v_rcp_iflag_f32_e32 v192, v174
	v_lshrrev_b32_e32 v174, 8, v190
	v_cndmask_b32_e64 v174, v174, v248, s[40:41]
	v_cvt_f32_ubyte0_e32 v174, v174
	v_rcp_iflag_f32_e32 v193, v174
	v_lshrrev_b32_e32 v174, 16, v190
	v_cndmask_b32_e64 v174, v174, v248, s[40:41]
	v_cvt_f32_ubyte0_e32 v174, v174
	v_pk_mul_f32 v[192:193], v[192:193], v[194:195]
	v_rcp_iflag_f32_e32 v194, v174
	v_lshrrev_b32_e32 v174, 24, v190
	v_cndmask_b32_e64 v174, v174, v248, s[40:41]
	v_cvt_f32_ubyte0_e32 v174, v174
	v_rcp_iflag_f32_e32 v195, v174
	v_cndmask_b32_e64 v174, v191, v248, s[40:41]
	v_pk_mul_f32 v[126:127], v[126:127], v[192:193]
	v_cvt_f32_ubyte3_e32 v193, v180
	v_cvt_f32_ubyte2_e32 v192, v180
	v_cvt_f32_ubyte0_e32 v174, v174
	v_pk_mul_f32 v[192:193], v[194:195], v[192:193]
	v_rcp_iflag_f32_e32 v194, v174
	v_lshrrev_b32_e32 v174, 8, v191
	v_cndmask_b32_e64 v174, v174, v248, s[40:41]
	v_cvt_f32_ubyte0_e32 v174, v174
	v_rcp_iflag_f32_e32 v195, v174
	v_lshrrev_b32_e32 v174, 16, v191
	v_cndmask_b32_e64 v174, v174, v248, s[40:41]
	v_cvt_f32_ubyte0_e32 v174, v174
	v_rcp_iflag_f32_e32 v190, v174
	v_lshrrev_b32_e32 v174, 24, v191
	v_cndmask_b32_e64 v174, v174, v248, s[40:41]
	v_cvt_f32_ubyte0_e32 v174, v174
	v_rcp_iflag_f32_e32 v191, v174
	v_pk_mul_f32 v[128:129], v[128:129], v[192:193]
	v_cvt_f32_ubyte1_e32 v193, v181
	v_cvt_f32_ubyte0_e32 v192, v181
	v_pk_mul_f32 v[192:193], v[194:195], v[192:193]
	s_cmp_lg_u32 s59, 2
	v_pk_mul_f32 v[122:123], v[122:123], v[192:193]
	v_cvt_f32_ubyte3_e32 v193, v181
	v_cvt_f32_ubyte2_e32 v192, v181
	v_pk_mul_f32 v[180:181], v[190:191], v[192:193]
	v_lshl_add_u64 v[130:131], s[30:31], 0, v[130:131]
	v_pk_mul_f32 v[124:125], v[124:125], v[180:181]
	s_cbranch_scc1 .LBB0_1382
	v_cvt_pk_bf16_f32 v190, v126, v127
	v_cvt_pk_bf16_f32 v191, v128, v129
	v_cvt_pk_bf16_f32 v192, v122, v123
	v_cvt_pk_bf16_f32 v193, v124, v125
	global_store_dwordx4 v[130:131], v[190:193], off

;     template <int QVV> __device__ __forceinline__ void run(f32x4 (&acc)[2][2][4][2], const Unit& u, int wr, int wc, int fr, int fq) const {
;     ...
;         for (int bj = 0; bj < 2; ++bj) {
;             u32x2 g0v[2][4], g1v[2][4];
; #pragma unroll
;             for (int ai = 0; ai < 2; ++ai)
; #pragma unroll
;                 for (int m = 0; m < 4; ++m) { if (ai >= nai) continue; const unsigned rr = (unsigned)(ai * HALF + m * 16);
;                     g0v[ai][m] = *(const u32x2*)(g0b + lg + rr * NGC + bj * HALF); g1v[ai][m] = *(const u32x2*)(g1b + lg + rr * NGC + bj * HALF); }
; #pragma unroll
;             for (int ai = 0; ai < 2; ++ai)
; #pragma unroll
;                 for (int m = 0; m < 4; ++m) { if (ai >= nai) continue; const unsigned rr = (unsigned)(ai * HALF + m * 16);
;                     float o[8];
; #pragma unroll
;                     for (int n = 0; n < 2; ++n)
; #pragma unroll
;                         for (int i = 0; i < 4; ++i) {
;                             const unsigned w0 = n == 0 ? g0v[ai][m].x : g0v[ai][m].y, w1 = (n == 0 ? g1v[ai][m].x : g1v[ai][m].y) | lm;
;                             const float q0 = (float)((w0 >> (8 * i)) & 255u), q1 = (float)((w1 >> (8 * i)) & 255u);
;                             const float f = q0 * __builtin_amdgcn_rcpf(q1);
;                             const float v = acc[ai][bj][m][n][i] * f; acc[ai][bj][m][n][i] = v; o[n * 4 + i] = v; }
;                     if (last) { u32x4 w; w.x = pk2(o[0], o[1]); w.y = pk2(o[2], o[3]); w.z = pk2(o[4], o[5]); w.w = pk2(o[6], o[7]);
;                         *(u32x4*)(ob + lw + (rr * DM + bj * HALF) * 2u) = w; } }
.LBB0_1396:
	global_load_dwordx2 v[164:165], v[134:135], off offset:128
	global_load_dwordx2 v[166:167], v[132:133], off offset:128
	v_add_co_u32_e32 v144, vcc, 0x400, v134
	s_nop 1
	v_addc_co_u32_e32 v145, vcc, 0, v135, vcc
	global_load_dwordx2 v[160:161], v[144:145], off offset:128
	v_add_co_u32_e32 v144, vcc, 0x400, v132
	s_nop 1
	v_addc_co_u32_e32 v145, vcc, 0, v133, vcc
	global_load_dwordx2 v[162:163], v[144:145], off offset:128
	v_add_co_u32_e32 v144, vcc, 0x800, v134
	s_nop 1
	v_addc_co_u32_e32 v145, vcc, 0, v135, vcc
	global_load_dwordx2 v[156:157], v[144:145], off offset:128
	v_add_co_u32_e32 v144, vcc, 0x800, v132
	s_nop 1
	v_addc_co_u32_e32 v145, vcc, 0, v133, vcc
	global_load_dwordx2 v[158:159], v[144:145], off offset:128
	v_add_co_u32_e32 v144, vcc, 0xc00, v134
	s_nop 1
	v_addc_co_u32_e32 v145, vcc, 0, v135, vcc
	global_load_dwordx2 v[152:153], v[144:145], off offset:128
	v_add_co_u32_e32 v144, vcc, 0xc00, v132
	s_nop 1
	v_addc_co_u32_e32 v145, vcc, 0, v133, vcc
	global_load_dwordx2 v[154:155], v[144:145], off offset:128
	global_load_dwordx2 v[148:149], v[140:141], off offset:128
	global_load_dwordx2 v[150:151], v[142:143], off offset:128
	v_add_co_u32_e32 v140, vcc, 0x1400, v134
	s_nop 1
	v_addc_co_u32_e32 v141, vcc, 0, v135, vcc
	global_load_dwordx2 v[144:145], v[140:141], off offset:128
	v_add_co_u32_e32 v140, vcc, 0x1400, v132
	s_nop 1
	v_addc_co_u32_e32 v141, vcc, 0, v133, vcc
	v_add_co_u32_e32 v134, vcc, 0x1800, v134
	global_load_dwordx2 v[146:147], v[140:141], off offset:128
	s_nop 0
	v_addc_co_u32_e32 v135, vcc, 0, v135, vcc
	v_add_co_u32_e32 v132, vcc, 0x1800, v132
	global_load_dwordx2 v[140:141], v[134:135], off offset:128
	s_nop 0
	v_addc_co_u32_e32 v133, vcc, 0, v133, vcc
	global_load_dwordx2 v[142:143], v[132:133], off offset:128
	s_nop 0
	global_load_dwordx2 v[132:133], v[136:137], off offset:128
	global_load_dwordx2 v[134:135], v[138:139], off offset:128
	s_and_b64 vcc, exec, s[42:43]
	s_waitcnt vmcnt(15)
	v_cvt_f32_ubyte1_e32 v139, v164
	s_waitcnt vmcnt(14)
	v_lshrrev_b32_e32 v137, 8, v166
	v_cndmask_b32_e64 v136, v166, v248, s[40:41]
	v_cndmask_b32_e64 v137, v137, v248, s[40:41]
	v_cvt_f32_ubyte0_e32 v136, v136
	v_cvt_f32_ubyte0_e32 v137, v137
	v_rcp_iflag_f32_e32 v136, v136
	v_rcp_iflag_f32_e32 v137, v137
	v_cvt_f32_ubyte0_e32 v138, v164
	v_pk_mul_f32 v[136:137], v[136:137], v[138:139]
	s_nop 0
	v_pk_mul_f32 v[94:95], v[94:95], v[136:137]
	v_lshrrev_b32_e32 v136, 16, v166
	v_lshrrev_b32_e32 v137, 24, v166
	v_cndmask_b32_e64 v136, v136, v248, s[40:41]
	v_cndmask_b32_e64 v137, v137, v248, s[40:41]
	v_cvt_f32_ubyte0_e32 v136, v136
	v_cvt_f32_ubyte0_e32 v137, v137
	v_rcp_iflag_f32_e32 v136, v136
	v_rcp_iflag_f32_e32 v137, v137
	v_cvt_f32_ubyte3_e32 v139, v164
	v_cvt_f32_ubyte2_e32 v138, v164
	v_pk_mul_f32 v[136:137], v[136:137], v[138:139]
	s_nop 0
	v_pk_mul_f32 v[96:97], v[96:97], v[136:137]
	v_lshrrev_b32_e32 v137, 8, v167
	v_cndmask_b32_e64 v136, v167, v248, s[40:41]
	v_cndmask_b32_e64 v137, v137, v248, s[40:41]
	v_cvt_f32_ubyte0_e32 v136, v136
	v_cvt_f32_ubyte0_e32 v137, v137
	v_rcp_iflag_f32_e32 v136, v136
	v_rcp_iflag_f32_e32 v137, v137
	v_cvt_f32_ubyte1_e32 v139, v165
	v_cvt_f32_ubyte0_e32 v138, v165
	v_pk_mul_f32 v[136:137], v[136:137], v[138:139]
	s_nop 0
	v_pk_mul_f32 v[90:91], v[90:91], v[136:137]
	v_lshrrev_b32_e32 v136, 16, v167
	v_lshrrev_b32_e32 v137, 24, v167
	v_cndmask_b32_e64 v136, v136, v248, s[40:41]
	v_cndmask_b32_e64 v137, v137, v248, s[40:41]
	v_cvt_f32_ubyte0_e32 v136, v136
	v_cvt_f32_ubyte0_e32 v137, v137
	v_rcp_iflag_f32_e32 v136, v136
	v_rcp_iflag_f32_e32 v137, v137
	v_cvt_f32_ubyte3_e32 v139, v165
	v_cvt_f32_ubyte2_e32 v138, v165
	v_pk_mul_f32 v[136:137], v[136:137], v[138:139]
	s_nop 0
	v_pk_mul_f32 v[92:93], v[92:93], v[136:137]
	s_cbranch_vccnz .LBB0_1398
	v_cvt_pk_bf16_f32 v136, v94, v95
	v_cvt_pk_bf16_f32 v137, v96, v97
	v_cvt_pk_bf16_f32 v138, v90, v91
	v_cvt_pk_bf16_f32 v139, v92, v93
	global_store_dwordx4 v[130:131], v[136:139], off offset:256

;     template <int QVV> __device__ __forceinline__ void run(f32x4 (&acc)[2][2][4][2], const Unit& u, int wr, int wc, int fr, int fq) const {
;         const int s = u.seg & 3, s1 = s < 2 ? s + 1 : s, hh = u.seg >> 2, r0 = u.pm * BM + (QVV == 2 ? (hh - 1) * HALF : 0); constexpr int nai = (QVV == 2) ? 1 : 2;
;         const char* g0b = (const char*)(G + (size_t)r0 * NGC + s * DM + u.pn * BM); const char* g1b = (const char*)(G + (size_t)r0 * NGC + s1 * DM + u.pn * BM);
;         char* ob = (char*)(O + (size_t)r0 * DM + u.pn * BM);
;         unsigned co = (unsigned)(wc * 32 + 8 * fq);
;         asm volatile("" : "+v"(co));
;         unsigned lg = (unsigned)((wr * 64 + fr) * NGC) + co, lw = ((unsigned)((wr * 64 + fr) * DM) + co) * 2u;
;         asm volatile("" : "+v"(lg), "+v"(lw));
;         const bool last = (s == 2);
;         const unsigned lm = last ? 0xffffffffu : 0u;
; #pragma unroll
;         for (int bj = 0; bj < 2; ++bj) {
;             u32x2 g0v[2][4], g1v[2][4];
; #pragma unroll
;             for (int ai = 0; ai < 2; ++ai)
; #pragma unroll
;                 for (int m = 0; m < 4; ++m) { if (ai >= nai) continue; const unsigned rr = (unsigned)(ai * HALF + m * 16);
;                     g0v[ai][m] = *(const u32x2*)(g0b + lg + rr * NGC + bj * HALF); g1v[ai][m] = *(const u32x2*)(g1b + lg + rr * NGC + bj * HALF); }
; #pragma unroll
;             for (int ai = 0; ai < 2; ++ai)
; #pragma unroll
;                 for (int m = 0; m < 4; ++m) { if (ai >= nai) continue; const unsigned rr = (unsigned)(ai * HALF + m * 16);
;                     float o[8];
; #pragma unroll
;                     for (int n = 0; n < 2; ++n)
; #pragma unroll
;                         for (int i = 0; i < 4; ++i) {
;                             const unsigned w0 = n == 0 ? g0v[ai][m].x : g0v[ai][m].y, w1 = (n == 0 ? g1v[ai][m].x : g1v[ai][m].y) | lm;
;                             const float q0 = (float)((w0 >> (8 * i)) & 255u), q1 = (float)((w1 >> (8 * i)) & 255u);
;                             const float f = q0 * __builtin_amdgcn_rcpf(q1);
;                             const float v = acc[ai][bj][m][n][i] * f; acc[ai][bj][m][n][i] = v; o[n * 4 + i] = v; }
;                     if (last) { u32x4 w; w.x = pk2(o[0], o[1]); w.y = pk2(o[2], o[3]); w.z = pk2(o[4], o[5]); w.w = pk2(o[6], o[7]);
;                         *(u32x4*)(ob + lw + (rr * DM + bj * HALF) * 2u) = w; } }
.LBB0_1432:
	s_and_b32 s38, s28, 3
	s_cmp_lt_u32 s38, 2
	s_cselect_b32 s39, 1, 0
	s_add_i32 s39, s38, s39
	s_mul_i32 s98, s29, 24
	s_add_i32 s98, s98, s27
	s_lshl_b32 s38, s38, 3
	s_lshl_b32 s39, s39, 3
	s_add_i32 s99, s98, s39
	s_add_i32 s98, s98, s38
	s_lshl_b32 s98, s98, 16
	s_lshl_b32 s99, s99, 16
	s_lshr_b32 s38, s28, 2
	s_add_i32 s38, s38, -1
	s_lshl_b32 s38, s38, 12
	s_add_i32 s98, s98, s38
	s_add_i32 s99, s99, s38
	s_and_b32 s46, s28, 3
	s_cmp_lt_u32 s46, 2
	s_cselect_b64 s[30:31], -1, 0
	s_cmp_lg_u64 s[30:31], 0
	s_addc_u32 s30, s46, 0
	s_lshl_b32 s28, s28, 5
	s_lshl_b32 s29, s29, 8
	s_and_b32 s28, s28, 0xffffff80
	s_add_i32 s28, s28, s29
	s_addk_i32 s28, 0xff80
	s_ashr_i32 s29, s28, 31
	s_mul_i32 s38, s28, 0x1800
	s_mul_hi_i32 s31, s28, 0x1800
	s_add_u32 s47, s9, s38
	s_addc_u32 s31, s10, s31
	s_lshl_b32 s38, s46, 11
	s_add_u32 s40, s47, s38
	s_addc_u32 s41, s31, 0
	s_lshl_b32 s38, s27, 8
	s_ashr_i32 s39, s38, 31
	s_add_u32 s40, s40, s38
	s_addc_u32 s41, s41, s39
	s_lshl_b32 s27, s30, 11
	v_mov_b32_e32 v66, v92
	s_add_u32 s27, s47, s27
	s_addc_u32 s31, s31, 0
	v_and_b32_e32 v174, 0x1c0, v0
	v_lshlrev_b32_e32 v174, 7, v174
	v_and_b32_e32 v72, 48, v0
	v_lshl_or_b32 v174, v72, 4, v174
	v_and_b32_e32 v72, 15, v0
	v_lshl_or_b32 v174, v72, 3, v174
	v_lshl_add_u32 v66, v66, 1, v94
	s_add_u32 s30, s27, s38
	s_addc_u32 s31, s31, s39
	s_add_u32 s40, s9, s98
	s_addc_u32 s41, s10, 0
	s_add_u32 s30, s9, s99
	s_addc_u32 s31, s10, 0
	global_load_dwordx2 v[84:85], v174, s[40:41]
	global_load_dwordx2 v[86:87], v174, s[30:31]
	s_lshl_b64 s[28:29], s[28:29], 12
	s_add_u32 s27, s44, s28
	s_addc_u32 s47, s45, s29
	s_lshl_b64 s[28:29], s[38:39], 1
	s_add_u32 s28, s27, s28
	v_lshl_add_u64 v[70:71], s[40:41], 0, v[174:175]
	s_mov_b32 s27, 0x400
	v_add_co_u32_e32 v72, vcc, s27, v70
	v_lshl_add_u64 v[68:69], s[30:31], 0, v[174:175]
	s_nop 0
	v_addc_co_u32_e32 v73, vcc, 0, v71, vcc
	global_load_dwordx2 v[80:81], v[72:73], off
	v_add_co_u32_e32 v72, vcc, s27, v68
	s_mov_b32 s27, 0x800
	s_nop 0
	v_addc_co_u32_e32 v73, vcc, 0, v69, vcc
	global_load_dwordx2 v[82:83], v[72:73], off
	v_add_co_u32_e32 v72, vcc, s27, v70
	s_addc_u32 s29, s47, s29
	s_nop 0
	v_addc_co_u32_e32 v73, vcc, 0, v71, vcc
	global_load_dwordx2 v[76:77], v[72:73], off
	v_add_co_u32_e32 v72, vcc, s27, v68
	s_mov_b32 s27, 0xc00
	s_nop 0
	v_addc_co_u32_e32 v73, vcc, 0, v69, vcc
	global_load_dwordx2 v[78:79], v[72:73], off
	v_add_co_u32_e32 v72, vcc, s27, v70
	s_cmp_eq_u32 s46, 2
	s_nop 0
	v_addc_co_u32_e32 v73, vcc, 0, v71, vcc
	v_add_co_u32_e32 v74, vcc, s27, v68
	global_load_dwordx2 v[72:73], v[72:73], off
	s_nop 0
	v_addc_co_u32_e32 v75, vcc, 0, v69, vcc
	global_load_dwordx2 v[74:75], v[74:75], off
	s_cselect_b64 s[38:39], -1, 0
	v_mov_b32_e32 v67, v175
	s_cmp_lg_u32 s46, 2
	v_lshl_add_u64 v[66:67], s[28:29], 0, v[66:67]
	s_waitcnt vmcnt(7)
	v_cvt_f32_ubyte1_e32 v103, v84
	s_waitcnt vmcnt(6)
	v_cndmask_b32_e64 v99, v86, v248, s[38:39]
	v_cvt_f32_ubyte0_e32 v99, v99
	v_rcp_iflag_f32_e32 v100, v99
	v_lshrrev_b32_e32 v99, 8, v86
	v_cndmask_b32_e64 v99, v99, v248, s[38:39]
	v_cvt_f32_ubyte0_e32 v99, v99
	v_rcp_iflag_f32_e32 v101, v99
	v_lshrrev_b32_e32 v99, 16, v86
	v_lshrrev_b32_e32 v86, 24, v86
	v_cvt_f32_ubyte0_e32 v102, v84
	v_cndmask_b32_e64 v99, v99, v248, s[38:39]
	v_cndmask_b32_e64 v86, v86, v248, s[38:39]
	v_pk_mul_f32 v[100:101], v[100:101], v[102:103]
	v_cvt_f32_ubyte0_e32 v99, v99
	v_cvt_f32_ubyte0_e32 v86, v86
	v_pk_mul_f32 v[62:63], v[62:63], v[100:101]
	v_rcp_iflag_f32_e32 v100, v99
	v_rcp_iflag_f32_e32 v101, v86
	v_cvt_f32_ubyte3_e32 v103, v84
	v_cvt_f32_ubyte2_e32 v102, v84
	v_cndmask_b32_e64 v84, v87, v248, s[38:39]
	v_pk_mul_f32 v[100:101], v[100:101], v[102:103]
	v_cvt_f32_ubyte0_e32 v84, v84
	v_pk_mul_f32 v[64:65], v[64:65], v[100:101]
	v_rcp_iflag_f32_e32 v100, v84
	v_lshrrev_b32_e32 v84, 8, v87
	v_cndmask_b32_e64 v84, v84, v248, s[38:39]
	v_cvt_f32_ubyte0_e32 v84, v84
	v_rcp_iflag_f32_e32 v101, v84
	v_lshrrev_b32_e32 v84, 16, v87
	v_cndmask_b32_e64 v84, v84, v248, s[38:39]
	v_cvt_f32_ubyte0_e32 v84, v84
	v_rcp_iflag_f32_e32 v86, v84
	v_lshrrev_b32_e32 v84, 24, v87
	v_cndmask_b32_e64 v84, v84, v248, s[38:39]
	v_cvt_f32_ubyte0_e32 v84, v84
	v_rcp_iflag_f32_e32 v87, v84
	v_cvt_f32_ubyte1_e32 v103, v85
	v_cvt_f32_ubyte0_e32 v102, v85
	v_pk_mul_f32 v[100:101], v[100:101], v[102:103]
	s_nop 0
	v_pk_mul_f32 v[58:59], v[58:59], v[100:101]
	v_cvt_f32_ubyte3_e32 v101, v85
	v_cvt_f32_ubyte2_e32 v100, v85
	v_pk_mul_f32 v[84:85], v[86:87], v[100:101]
	s_nop 0
	v_pk_mul_f32 v[60:61], v[60:61], v[84:85]
	s_cbranch_scc1 .LBB0_1434
	v_cvt_pk_bf16_f32 v84, v62, v63
	v_cvt_pk_bf16_f32 v85, v64, v65
	v_cvt_pk_bf16_f32 v86, v58, v59
	v_cvt_pk_bf16_f32 v87, v60, v61
	global_store_dwordx4 v[66:67], v[84:87], off

;     template <int QVV> __device__ __forceinline__ void run(f32x4 (&acc)[2][2][4][2], const Unit& u, int wr, int wc, int fr, int fq) const {
;     ...
;         for (int bj = 0; bj < 2; ++bj) {
;             u32x2 g0v[2][4], g1v[2][4];
; #pragma unroll
;             for (int ai = 0; ai < 2; ++ai)
; #pragma unroll
;                 for (int m = 0; m < 4; ++m) { if (ai >= nai) continue; const unsigned rr = (unsigned)(ai * HALF + m * 16);
;                     g0v[ai][m] = *(const u32x2*)(g0b + lg + rr * NGC + bj * HALF); g1v[ai][m] = *(const u32x2*)(g1b + lg + rr * NGC + bj * HALF); }
; #pragma unroll
;             for (int ai = 0; ai < 2; ++ai)
; #pragma unroll
;                 for (int m = 0; m < 4; ++m) { if (ai >= nai) continue; const unsigned rr = (unsigned)(ai * HALF + m * 16);
;                     float o[8];
; #pragma unroll
;                     for (int n = 0; n < 2; ++n)
; #pragma unroll
;                         for (int i = 0; i < 4; ++i) {
;                             const unsigned w0 = n == 0 ? g0v[ai][m].x : g0v[ai][m].y, w1 = (n == 0 ? g1v[ai][m].x : g1v[ai][m].y) | lm;
;                             const float q0 = (float)((w0 >> (8 * i)) & 255u), q1 = (float)((w1 >> (8 * i)) & 255u);
;                             const float f = q0 * __builtin_amdgcn_rcpf(q1);
;                             const float v = acc[ai][bj][m][n][i] * f; acc[ai][bj][m][n][i] = v; o[n * 4 + i] = v; }
;                     if (last) { u32x4 w; w.x = pk2(o[0], o[1]); w.y = pk2(o[2], o[3]); w.z = pk2(o[4], o[5]); w.w = pk2(o[6], o[7]);
;                         *(u32x4*)(ob + lw + (rr * DM + bj * HALF) * 2u) = w; } }
.LBB0_1440:
	global_load_dwordx2 v[80:81], v[70:71], off offset:128
	global_load_dwordx2 v[82:83], v[68:69], off offset:128
	v_add_co_u32_e32 v72, vcc, 0x400, v70
	s_waitcnt vmcnt(1)
	v_cvt_f32_ubyte1_e32 v87, v80
	v_addc_co_u32_e32 v73, vcc, 0, v71, vcc
	global_load_dwordx2 v[76:77], v[72:73], off offset:128
	v_add_co_u32_e32 v72, vcc, 0x400, v68
	s_waitcnt vmcnt(1)
	v_lshrrev_b32_e32 v85, 8, v82
	v_addc_co_u32_e32 v73, vcc, 0, v69, vcc
	global_load_dwordx2 v[78:79], v[72:73], off offset:128
	v_add_co_u32_e32 v72, vcc, 0x800, v70
	v_cndmask_b32_e64 v84, v82, v248, s[38:39]
	s_nop 0
	v_addc_co_u32_e32 v73, vcc, 0, v71, vcc
	v_add_co_u32_e32 v74, vcc, 0x800, v68
	global_load_dwordx2 v[72:73], v[72:73], off offset:128
	s_nop 0
	v_addc_co_u32_e32 v75, vcc, 0, v69, vcc
	v_add_co_u32_e32 v70, vcc, 0xc00, v70
	global_load_dwordx2 v[74:75], v[74:75], off offset:128
	s_nop 0
	v_addc_co_u32_e32 v71, vcc, 0, v71, vcc
	v_add_co_u32_e32 v68, vcc, 0xc00, v68
	global_load_dwordx2 v[70:71], v[70:71], off offset:128
	s_nop 0
	v_addc_co_u32_e32 v69, vcc, 0, v69, vcc
	global_load_dwordx2 v[68:69], v[68:69], off offset:128
	v_cndmask_b32_e64 v85, v85, v248, s[38:39]
	v_cvt_f32_ubyte0_e32 v84, v84
	v_cvt_f32_ubyte0_e32 v85, v85
	v_rcp_iflag_f32_e32 v84, v84
	v_rcp_iflag_f32_e32 v85, v85
	v_cvt_f32_ubyte0_e32 v86, v80
	s_and_b64 vcc, exec, s[40:41]
	v_pk_mul_f32 v[84:85], v[84:85], v[86:87]
	s_nop 0
	v_pk_mul_f32 v[30:31], v[30:31], v[84:85]
	v_lshrrev_b32_e32 v84, 16, v82
	v_lshrrev_b32_e32 v82, 24, v82
	v_cndmask_b32_e64 v84, v84, v248, s[38:39]
	v_cndmask_b32_e64 v82, v82, v248, s[38:39]
	v_cvt_f32_ubyte0_e32 v84, v84
	v_cvt_f32_ubyte0_e32 v82, v82
	v_rcp_iflag_f32_e32 v84, v84
	v_rcp_iflag_f32_e32 v85, v82
	v_cvt_f32_ubyte3_e32 v87, v80
	v_cvt_f32_ubyte2_e32 v86, v80
	v_cndmask_b32_e64 v80, v83, v248, s[38:39]
	v_pk_mul_f32 v[84:85], v[84:85], v[86:87]
	v_cvt_f32_ubyte0_e32 v80, v80
	v_pk_mul_f32 v[32:33], v[32:33], v[84:85]
	v_rcp_iflag_f32_e32 v84, v80
	v_lshrrev_b32_e32 v80, 8, v83
	v_cndmask_b32_e64 v80, v80, v248, s[38:39]
	v_cvt_f32_ubyte0_e32 v80, v80
	v_rcp_iflag_f32_e32 v85, v80
	v_lshrrev_b32_e32 v80, 16, v83
	v_cndmask_b32_e64 v80, v80, v248, s[38:39]
	v_cvt_f32_ubyte0_e32 v80, v80
	v_rcp_iflag_f32_e32 v82, v80
	v_lshrrev_b32_e32 v80, 24, v83
	v_cndmask_b32_e64 v80, v80, v248, s[38:39]
	v_cvt_f32_ubyte0_e32 v80, v80
	v_rcp_iflag_f32_e32 v83, v80
	v_cvt_f32_ubyte1_e32 v87, v81
	v_cvt_f32_ubyte0_e32 v86, v81
	v_pk_mul_f32 v[84:85], v[84:85], v[86:87]
	s_nop 0
	v_pk_mul_f32 v[26:27], v[26:27], v[84:85]
	v_cvt_f32_ubyte3_e32 v85, v81
	v_cvt_f32_ubyte2_e32 v84, v81
	v_pk_mul_f32 v[80:81], v[82:83], v[84:85]
	s_nop 0
	v_pk_mul_f32 v[28:29], v[28:29], v[80:81]
	s_cbranch_vccnz .LBB0_1442
	v_cvt_pk_bf16_f32 v80, v30, v31
	v_cvt_pk_bf16_f32 v81, v32, v33
	v_cvt_pk_bf16_f32 v82, v26, v27
	v_cvt_pk_bf16_f32 v83, v28, v29
	global_store_dwordx4 v[66:67], v[80:83], off offset:256
